# ret_out: L2 prefetch (dummy dword loads per 64B sector) of the next task's state images and q/k/v/gate rows, on top of trim+defer
# speedup vs baseline: 1.0007x; 1.0007x over previous
; __device__ __forceinline__ void ret_out(const bf16_t* proj, const float* cosT, const float* sinT, const float* decay, const float* gn_g, const float* gn_b,
;                         const bf16_t* states, bf16_t* mix, unsigned char* lds, int tid, int bx) {
;     ...
;     for (int task = bx; task < 1536; task += gridDim.x) {
;         int tl = tid; asm volatile("" : "+v"(tl));
;         const int lane = tl & 63, fr = lane & 15, fq = lane >> 4, c = tl >> 2, part = tl & 3, cw = c ^ (part << 4);
;         const int n = task & 31, bh = task >> 5, b = bh / 6, h = bh % 6;
;         const float lgf2 = -__expf(decay[h]) * 1.4426950408889634f, lgb2 = -__expf(decay[6 + h]) * 1.4426950408889634f;
;         const int cq = 16 * wave + fr, tq = n * 128 + cq; const size_t rowq = (size_t)(b * SEQ + tq) * LDR;
;         __syncthreads();
;         {
;             const char* spb = (const char*)(states + ((size_t)(bh * 2) * 32 + n) * 16384);
; #pragma unroll
;             for (int dir = 0; dir < 2; ++dir)
; #pragma unroll
;                 for (int q4 = 0; q4 < 4; ++q4) { const int pc = wave + 8 * q4, e = 4 * pc + (lane >> 4), ch = (lane & 15) ^ (e & 15);
;                     __builtin_amdgcn_global_load_lds((const unsigned*)(spb + (size_t)dir * (32 * 16384 * 2) + e * 256 + ch * 16), (LAS unsigned*)(ldsl + ST_OFF + dir * 32768 + pc * 1024), 16, 0, 0); }
;         }
;         u32x4 qr[4]; float4 qc[2][2], qs[2][2];
;         { const bf16_t* qp = proj + rowq + h * 128 + 8 * fq;
; #pragma unroll
;           for (int ks = 0; ks < 4; ++ks) qr[ks] = *(const u32x4*)(qp + 32 * ks);
; #pragma unroll
;           for (int k2 = 0; k2 < 2; ++k2) { const float* cp = cosT + tq * 64 + 32 * k2 + 8 * fq; const float* snp = sinT + tq * 64 + 32 * k2 + 8 * fq;
;               qc[k2][0] = *(const float4*)cp; qc[k2][1] = *(const float4*)(cp + 4); qs[k2][0] = *(const float4*)snp; qs[k2][1] = *(const float4*)(snp + 4); } }
;         {
;             const int t = n * 128 + c; const size_t row = (size_t)(b * SEQ + t) * LDR;
;             const bf16_t* kp = proj + row + 768 + h * 128 + 16 * part;
;             const u32x4 k1a = *(const u32x4*)kp, k1b = *(const u32x4*)(kp + 8), k2a = *(const u32x4*)(kp + 64), k2b = *(const u32x4*)(kp + 72);
;             const float* cp = cosT + t * 64 + 16 * part; const float* snp = sinT + t * 64 + 16 * part;
;             const int cpv = tl >> 3, p8v = tl & 7, c0v = 2 * cpv;
.LBB0_189:
	s_ashr_i32 s15, s49, 5
	s_mul_hi_i32 s0, s15, 0x2aaaaaab
	s_lshr_b32 s1, s0, 31
	s_add_i32 s17, s0, s1
	s_mul_i32 s0, s17, 6
	s_sub_i32 s36, s15, s0
	s_ashr_i32 s37, s36, 31
	s_and_b32 s14, s49, 31
	s_lshl_b64 s[0:1], s[36:37], 2
	s_add_u32 s0, s6, s0
	v_mov_b32_e32 v22, v60
	s_addc_u32 s1, s19, s1
	s_load_dword s100, s[0:1], 0x0
	s_load_dword s101, s[0:1], 0x18
	s_lshl_b32 s18, s14, 7
	s_lshl_b32 s37, s17, 12
	v_bfe_u32 v84, v22, 4, 2
	v_bitop3_b32 v4, v84, v22, s29 bitop3:0x36
	v_lshlrev_b32_e32 v4, 4, v4
	v_and_b32_e32 v154, 0xf0, v4
	v_bitop3_b32 v4, v84, v22, s31 bitop3:0x36
	v_lshlrev_b32_e32 v4, 4, v4
	v_and_b32_e32 v4, 0xf0, v4
	v_mov_b32_e32 v5, v155
	v_bitop3_b32 v10, v84, v22, s35 bitop3:0x36
	v_lshlrev_b32_e32 v10, 4, v10
	v_and_b32_e32 v10, 0xf0, v10
	v_mov_b32_e32 v11, v155
	v_bitop3_b32 v14, v84, v22, s45 bitop3:0x36
	v_lshlrev_b32_e32 v14, 4, v14
	v_and_b32_e32 v14, 0xf0, v14
	v_mov_b32_e32 v15, v155
	v_and_b32_e32 v83, 15, v22
	v_or_b32_e32 v86, s28, v83
	v_add_u32_e32 v18, s18, v86
	v_add_u32_e32 v80, s37, v18
	v_mov_b64_e32 v[40:41], s[22:23]
	v_lshlrev_b32_e32 v18, 6, v18
	v_lshlrev_b32_e32 v62, 4, v84
	v_mov_b32_e32 v63, v155
	v_ashrrev_i32_e32 v19, 31, v18
	v_lshlrev_b64 v[20:21], 2, v[18:19]
	v_lshl_add_u64 v[18:19], s[38:39], 0, v[20:21]
	v_lshlrev_b32_e32 v24, 5, v84
	v_mov_b32_e32 v25, v155
	v_lshl_add_u64 v[20:21], s[40:41], 0, v[20:21]
	v_lshl_add_u64 v[18:19], v[18:19], 0, v[24:25]
	v_lshl_add_u64 v[20:21], v[20:21], 0, v[24:25]
	v_lshlrev_b32_e32 v26, 4, v22
	v_and_b32_e32 v108, 48, v26
	v_lshlrev_b32_e32 v46, 2, v108
	v_mov_b32_e32 v47, v155
	v_lshlrev_b32_e32 v100, 1, v108
	v_mov_b32_e32 v101, v155
	v_lshrrev_b32_e32 v85, 4, v22
	v_ashrrev_i32_e32 v81, 31, v80
	s_waitcnt lgkmcnt(0)
	v_mov_b32_e32 v0, s100
	v_mul_f32_e32 v0, 0x3fb8aa3b, v0
	v_exp_f32_e32 v16, v0
	s_lshl_b32 s0, s15, 1
	s_ashr_i32 s1, s0, 31
	s_lshl_b64 s[0:1], s[0:1], 20
	s_add_u32 s0, s24, s0
	s_addc_u32 s1, s25, s1
	s_lshl_b32 s14, s14, 15
	s_add_u32 s14, s0, s14
	s_addc_u32 s15, s1, 0
	s_add_i32 m0, s55, s30
	s_barrier
	v_mul_f32_e32 v87, 0xbfb8aa3b, v16
	v_mov_b32_e32 v0, s101
	v_mul_f32_e32 v0, 0x3fb8aa3b, v0
	v_exp_f32_e32 v23, v0
	v_or_b32_e32 v0, s29, v84
	v_lshlrev_b32_e32 v0, 8, v0
	v_ashrrev_i32_e32 v1, 31, v0
	v_lshl_add_u64 v[2:3], s[14:15], 0, v[0:1]
	v_lshl_add_u64 v[2:3], v[2:3], 0, v[154:155]
	global_load_lds_dwordx4 v[2:3], off
	v_or_b32_e32 v2, s31, v84
	v_lshlrev_b32_e32 v2, 8, v2
	v_ashrrev_i32_e32 v3, 31, v2
	v_lshl_add_u64 v[6:7], s[14:15], 0, v[2:3]
	v_lshl_add_u64 v[6:7], v[6:7], 0, v[4:5]
	s_add_i32 m0, s55, s34
	s_nop 0
	global_load_lds_dwordx4 v[6:7], off
	v_or_b32_e32 v6, s35, v84
	v_lshlrev_b32_e32 v6, 8, v6
	v_ashrrev_i32_e32 v7, 31, v6
	v_lshl_add_u64 v[8:9], s[14:15], 0, v[6:7]
	v_lshl_add_u64 v[8:9], v[8:9], 0, v[10:11]
	s_add_i32 m0, s55, s44
	s_nop 0
	global_load_lds_dwordx4 v[8:9], off
	v_or_b32_e32 v8, s45, v84
	v_lshlrev_b32_e32 v8, 8, v8
	s_add_i32 m0, s55, s48
	v_ashrrev_i32_e32 v9, 31, v8
	s_add_u32 s0, s14, 0x100000
	v_lshl_add_u64 v[12:13], s[14:15], 0, v[8:9]
	s_addc_u32 s1, s15, 0
	v_lshl_add_u64 v[12:13], v[12:13], 0, v[14:15]
	v_lshl_add_u64 v[0:1], s[0:1], 0, v[0:1]
	global_load_lds_dwordx4 v[12:13], off
	v_lshl_add_u64 v[0:1], v[0:1], 0, v[154:155]
	s_add_i32 m0, s50, s30
	v_lshlrev_b32_e32 v154, 3, v84
	global_load_lds_dwordx4 v[0:1], off
	v_lshl_add_u64 v[0:1], s[0:1], 0, v[2:3]
	v_lshl_add_u64 v[0:1], v[0:1], 0, v[4:5]
	s_add_i32 m0, s50, s34
	s_add_i32 s49, s49, s3
	global_load_lds_dwordx4 v[0:1], off
	v_lshl_add_u64 v[0:1], s[0:1], 0, v[6:7]
	v_lshl_add_u64 v[0:1], v[0:1], 0, v[10:11]
	s_add_i32 m0, s50, s44
	s_nop 0
	global_load_lds_dwordx4 v[0:1], off
	v_lshl_add_u64 v[0:1], s[0:1], 0, v[8:9]
	v_lshl_add_u64 v[0:1], v[0:1], 0, v[14:15]
	s_add_i32 m0, s50, s48
	s_nop 0
	global_load_lds_dwordx4 v[0:1], off
	v_mad_i64_i32 v[0:1], s[0:1], v80, s59, v[40:41]
	s_lshl_b32 s0, s36, 7
	s_ashr_i32 s1, s0, 31
	s_lshl_b64 s[46:47], s[0:1], 1
	v_lshl_add_u64 v[16:17], v[0:1], 0, s[46:47]
	v_lshl_add_u64 v[12:13], v[16:17], 0, v[62:63]
	v_ashrrev_i32_e32 v63, 2, v22
	v_add_u32_e32 v42, s18, v63
	v_add_u32_e32 v24, s37, v42
	v_lshlrev_b32_e32 v42, 6, v42
	v_ashrrev_i32_e32 v43, 31, v42
	v_lshlrev_b64 v[42:43], 2, v[42:43]
	v_mad_i64_i32 v[24:25], s[0:1], v24, s59, v[40:41]
	v_lshl_add_u64 v[44:45], s[38:39], 0, v[42:43]
	v_lshl_add_u64 v[42:43], s[40:41], 0, v[42:43]
	v_lshl_add_u64 v[96:97], v[42:43], 0, v[46:47]
	v_and_b32_e32 v42, -2, v63
	s_or_b32 s0, s37, s18
	v_lshl_add_u64 v[24:25], v[24:25], 0, s[46:47]
	v_add_u32_e32 v42, s0, v42
	v_lshl_add_u64 v[36:37], v[24:25], 0, v[100:101]
	v_and_b32_e32 v101, 7, v22
	v_mad_i64_i32 v[40:41], s[0:1], v42, s59, v[40:41]
	v_lshl_add_u64 v[40:41], v[40:41], 0, s[46:47]
	v_lshlrev_b32_e32 v42, 5, v101
	v_mov_b32_e32 v43, v155
	v_lshl_add_u64 v[48:49], v[40:41], 0, v[42:43]
	s_mov_b64 s[0:1], 0x2600
	global_load_dwordx4 v[0:3], v[12:13], off
	global_load_dwordx4 v[8:11], v[12:13], off offset:64
	global_load_dwordx4 v[4:7], v[12:13], off offset:128
	s_nop 0
	global_load_dwordx4 v[12:15], v[12:13], off offset:192
	s_nop 0
	global_load_dwordx4 v[24:27], v[36:37], off offset:1552
	global_load_dwordx4 v[28:31], v[36:37], off offset:1536
	global_load_dwordx4 v[32:35], v[36:37], off offset:1680
	s_nop 0
	global_load_dwordx4 v[36:39], v[36:37], off offset:1664
	v_lshl_add_u64 v[72:73], v[44:45], 0, v[46:47]
	global_load_dwordx4 v[40:43], v[48:49], off offset:3088
	global_load_dwordx4 v[44:47], v[48:49], off offset:3072
	v_lshl_add_u64 v[52:53], v[48:49], 0, s[0:1]
	v_add_co_u32_e32 v48, vcc, s98, v48
	s_mov_b64 s[0:1], 0x1200
	s_nop 0
	v_addc_co_u32_e32 v49, vcc, 0, v49, vcc
	global_load_dwordx4 v[48:51], v[48:49], off offset:1536
	s_nop 0
	global_load_dwordx4 v[52:55], v[52:53], off offset:16
	s_nop 0
	global_load_dwordx4 v[56:59], v[72:73], off offset:48
	global_load_dwordx4 v[64:67], v[72:73], off offset:32
	global_load_dwordx4 v[68:71], v[72:73], off offset:16
	s_nop 0
	global_load_dwordx4 v[72:75], v[72:73], off
	s_nop 0
	global_load_dwordx4 v[76:79], v[96:97], off offset:48
	global_load_dwordx4 v[88:91], v[96:97], off offset:32
	global_load_dwordx4 v[92:95], v[96:97], off offset:16
	s_nop 0
	global_load_dwordx4 v[96:99], v[96:97], off
	global_load_dwordx4 v[184:187], v[18:19], off offset:16
	global_load_dwordx4 v[188:191], v[18:19], off
	global_load_dwordx4 v[192:195], v[20:21], off offset:16
	global_load_dwordx4 v[196:199], v[20:21], off
	global_load_dwordx4 v[200:203], v[18:19], off offset:144
	global_load_dwordx4 v[204:207], v[18:19], off offset:128
	global_load_dwordx4 v[208:211], v[20:21], off offset:144
	global_load_dwordx4 v[212:215], v[20:21], off offset:128
	s_waitcnt vmcnt(0)
; __device__ __forceinline__ void ret_out(const bf16_t* proj, const float* cosT, const float* sinT, const float* decay, const float* gn_g, const float* gn_b,
;                         const bf16_t* states, bf16_t* mix, unsigned char* lds, int tid, int bx) {
;     ...
;         {
;             const int t = n * 128 + c; const size_t row = (size_t)(b * SEQ + t) * LDR;
;             const bf16_t* kp = proj + row + 768 + h * 128 + 16 * part;
;             const u32x4 k1a = *(const u32x4*)kp, k1b = *(const u32x4*)(kp + 8), k2a = *(const u32x4*)(kp + 64), k2b = *(const u32x4*)(kp + 72);
;             const float* cp = cosT + t * 64 + 16 * part; const float* snp = sinT + t * 64 + 16 * part;
;             const int cpv = tl >> 3, p8v = tl & 7, c0v = 2 * cpv;
;             const bf16_t* vp = proj + (size_t)(b * SEQ + n * 128 + c0v) * LDR + 1536 + h * 128 + 16 * p8v;
;             u32x4 vv[4];
;             vv[0] = *(const u32x4*)vp; vv[1] = *(const u32x4*)(vp + 8); vv[2] = *(const u32x4*)(vp + LDR); vv[3] = *(const u32x4*)(vp + LDR + 8);
;             float cs[16], sn[16];
; #pragma unroll
;             for (int q4 = 0; q4 < 4; ++q4) { const float4 cv = *(const float4*)(cp + 4 * q4), sv = *(const float4*)(snp + 4 * q4);
;                 cs[4 * q4] = cv.x; cs[4 * q4 + 1] = cv.y; cs[4 * q4 + 2] = cv.z; cs[4 * q4 + 3] = cv.w; sn[4 * q4] = sv.x; sn[4 * q4 + 1] = sv.y; sn[4 * q4 + 2] = sv.z; sn[4 * q4 + 3] = sv.w; }
;             const unsigned k1w[8] = {k1a.x, k1a.y, k1a.z, k1a.w, k1b.x, k1b.y, k1b.z, k1b.w}, k2w[8] = {k2a.x, k2a.y, k2a.z, k2a.w, k2b.x, k2b.y, k2b.z, k2b.w};
;             unsigned r1[8], r2[8];
; #pragma unroll
;             for (int w2 = 0; w2 < 8; ++w2) {
;                 const float a1 = bf_lo(k1w[w2]), b1 = bf_hi(k1w[w2]), a2 = bf_lo(k2w[w2]), b2 = bf_hi(k2w[w2]);
;                 r1[w2] = cvt_pk_bf16(a1 * cs[2 * w2] - a2 * sn[2 * w2], b1 * cs[2 * w2 + 1] - b2 * sn[2 * w2 + 1]);
;                 r2[w2] = cvt_pk_bf16(a1 * sn[2 * w2] + a2 * cs[2 * w2], b1 * sn[2 * w2 + 1] + b2 * cs[2 * w2 + 1]);
;             }
;             *(u32x4*)(Kl + c * LP + 16 * part) = (u32x4){r1[0], r1[1], r1[2], r1[3]}; *(u32x4*)(Kl + c * LP + 16 * part + 8) = (u32x4){r1[4], r1[5], r1[6], r1[7]};
;             *(u32x4*)(Kl + c * LP + 64 + 16 * part) = (u32x4){r2[0], r2[1], r2[2], r2[3]}; *(u32x4*)(Kl + c * LP + 64 + 16 * part + 8) = (u32x4){r2[4], r2[5], r2[6], r2[7]};
	v_lshlrev_b32_e32 v102, 16, v28
	v_and_b32_e32 v103, 0xffff0000, v28
	v_lshlrev_b32_e32 v104, 16, v36
	v_and_b32_e32 v105, 0xffff0000, v36
	v_pk_mul_f32 v[106:107], v[96:97], v[104:105]
	v_pk_mul_f32 v[96:97], v[96:97], v[102:103]
	v_pk_fma_f32 v[106:107], v[72:73], v[102:103], v[106:107] neg_lo:[0,0,1] neg_hi:[0,0,1]
	v_pk_fma_f32 v[72:73], v[72:73], v[104:105], v[96:97]
	v_lshlrev_b32_e32 v96, 16, v37
	v_and_b32_e32 v97, 0xffff0000, v37
	v_cvt_pk_bf16_f32 v36, v72, v73
	v_lshlrev_b32_e32 v72, 16, v29
	v_and_b32_e32 v73, 0xffff0000, v29
	v_pk_mul_f32 v[102:103], v[98:99], v[96:97]
	v_cvt_pk_bf16_f32 v28, v106, v107
	v_pk_fma_f32 v[102:103], v[74:75], v[72:73], v[102:103] neg_lo:[0,0,1] neg_hi:[0,0,1]
	v_pk_mul_f32 v[72:73], v[98:99], v[72:73]
	v_cvt_pk_bf16_f32 v29, v102, v103
	v_pk_fma_f32 v[72:73], v[74:75], v[96:97], v[72:73]
	v_lshlrev_b32_e32 v74, 16, v38
	v_and_b32_e32 v75, 0xffff0000, v38
	v_cvt_pk_bf16_f32 v37, v72, v73
	v_lshlrev_b32_e32 v72, 16, v30
	v_and_b32_e32 v73, 0xffff0000, v30
	v_pk_mul_f32 v[96:97], v[92:93], v[74:75]
	s_nop 0
	v_pk_fma_f32 v[96:97], v[68:69], v[72:73], v[96:97] neg_lo:[0,0,1] neg_hi:[0,0,1]
	v_pk_mul_f32 v[72:73], v[92:93], v[72:73]
	v_cvt_pk_bf16_f32 v30, v96, v97
	v_pk_fma_f32 v[68:69], v[68:69], v[74:75], v[72:73]
	v_lshlrev_b32_e32 v72, 16, v39
	v_and_b32_e32 v73, 0xffff0000, v39
	v_cvt_pk_bf16_f32 v38, v68, v69
	v_lshlrev_b32_e32 v68, 16, v31
	v_and_b32_e32 v69, 0xffff0000, v31
	v_pk_mul_f32 v[74:75], v[94:95], v[72:73]
	s_nop 0
	v_pk_fma_f32 v[74:75], v[70:71], v[68:69], v[74:75] neg_lo:[0,0,1] neg_hi:[0,0,1]
	v_pk_mul_f32 v[68:69], v[94:95], v[68:69]
	v_cvt_pk_bf16_f32 v31, v74, v75
	v_pk_fma_f32 v[68:69], v[70:71], v[72:73], v[68:69]
	v_lshlrev_b32_e32 v70, 16, v32
	v_and_b32_e32 v71, 0xffff0000, v32
	v_cvt_pk_bf16_f32 v39, v68, v69
	v_lshlrev_b32_e32 v68, 16, v24
	v_and_b32_e32 v69, 0xffff0000, v24
	v_pk_mul_f32 v[72:73], v[88:89], v[70:71]
	s_nop 0
	v_pk_fma_f32 v[72:73], v[64:65], v[68:69], v[72:73] neg_lo:[0,0,1] neg_hi:[0,0,1]
	v_pk_mul_f32 v[68:69], v[88:89], v[68:69]
	v_cvt_pk_bf16_f32 v24, v72, v73
	v_pk_fma_f32 v[64:65], v[64:65], v[70:71], v[68:69]
	v_lshlrev_b32_e32 v68, 16, v33
	v_and_b32_e32 v69, 0xffff0000, v33
	v_cvt_pk_bf16_f32 v32, v64, v65
	v_lshlrev_b32_e32 v64, 16, v25
	v_and_b32_e32 v65, 0xffff0000, v25
	v_pk_mul_f32 v[70:71], v[90:91], v[68:69]
	s_nop 0
	v_pk_fma_f32 v[70:71], v[66:67], v[64:65], v[70:71] neg_lo:[0,0,1] neg_hi:[0,0,1]
	v_pk_mul_f32 v[64:65], v[90:91], v[64:65]
	v_cvt_pk_bf16_f32 v25, v70, v71
	v_pk_fma_f32 v[64:65], v[66:67], v[68:69], v[64:65]
	v_lshlrev_b32_e32 v66, 16, v34
	v_and_b32_e32 v67, 0xffff0000, v34
	v_cvt_pk_bf16_f32 v33, v64, v65
	v_lshlrev_b32_e32 v64, 16, v26
	v_and_b32_e32 v65, 0xffff0000, v26
	v_pk_mul_f32 v[68:69], v[76:77], v[66:67]
	s_nop 0
	v_pk_fma_f32 v[68:69], v[56:57], v[64:65], v[68:69] neg_lo:[0,0,1] neg_hi:[0,0,1]
	v_pk_mul_f32 v[64:65], v[76:77], v[64:65]
	v_cvt_pk_bf16_f32 v26, v68, v69
	v_pk_fma_f32 v[56:57], v[56:57], v[66:67], v[64:65]
	v_lshlrev_b32_e32 v64, 16, v35
	v_and_b32_e32 v65, 0xffff0000, v35
	v_cvt_pk_bf16_f32 v34, v56, v57
	v_lshlrev_b32_e32 v56, 16, v27
	v_and_b32_e32 v57, 0xffff0000, v27
	v_pk_mul_f32 v[66:67], v[78:79], v[64:65]
	s_nop 0
	v_pk_fma_f32 v[66:67], v[58:59], v[56:57], v[66:67] neg_lo:[0,0,1] neg_hi:[0,0,1]
	v_pk_mul_f32 v[56:57], v[78:79], v[56:57]
	v_cvt_pk_bf16_f32 v27, v66, v67
	v_pk_fma_f32 v[56:57], v[58:59], v[64:65], v[56:57]
	s_nop 0
	v_cvt_pk_bf16_f32 v35, v56, v57
	v_mul_lo_u32 v56, v63, s52
	v_add3_u32 v56, 0, v56, v100
	ds_write_b128 v56, v[28:31]
	ds_write_b128 v56, v[24:27] offset:16
	ds_write_b128 v56, v[36:39] offset:128
	ds_write_b128 v56, v[32:35] offset:144
	v_bitop3_b32 v25, v63, v108, -2 bitop3:0x6c
	v_mul_u32_u24_e32 v24, 0x1100, v101
	v_lshlrev_b32_e32 v25, 1, v25
	v_add3_u32 v24, 0, v24, v25
	v_and_b32_e32 v25, 0xffff, v44
	v_lshrrev_b32_e32 v26, 16, v44
	v_lshl_or_b32 v25, v48, 16, v25
	v_and_or_b32 v26, v48, s51, v26
	v_add_u32_e32 v27, 0x8800, v24
	ds_write2_b32 v27, v25, v26 offset1:68
	v_and_b32_e32 v25, 0xffff, v45
	v_lshrrev_b32_e32 v26, 16, v45
	v_lshl_or_b32 v25, v49, 16, v25
	v_and_or_b32 v26, v49, s51, v26
	ds_write2_b32 v27, v25, v26 offset0:136 offset1:204
	v_and_b32_e32 v25, 0xffff, v46
	v_lshrrev_b32_e32 v26, 16, v46
	v_lshl_or_b32 v25, v50, 16, v25
	v_and_or_b32 v26, v50, s51, v26
	v_add_u32_e32 v27, 0x8c00, v24
	ds_write2_b32 v27, v25, v26 offset0:16 offset1:84
	v_and_b32_e32 v25, 0xffff, v47
	v_lshrrev_b32_e32 v26, 16, v47
	v_lshl_or_b32 v25, v51, 16, v25
	v_and_or_b32 v26, v51, s51, v26
	ds_write2_b32 v27, v25, v26 offset0:152 offset1:220
	v_and_b32_e32 v25, 0xffff, v40
	v_lshrrev_b32_e32 v26, 16, v40
	v_lshl_or_b32 v25, v52, 16, v25
	v_and_or_b32 v26, v52, s51, v26
	v_add_u32_e32 v27, 0x9000, v24
	ds_write2_b32 v27, v25, v26 offset0:32 offset1:100
	v_and_b32_e32 v25, 0xffff, v41
	v_lshrrev_b32_e32 v26, 16, v41
	v_lshl_or_b32 v25, v53, 16, v25
	v_and_or_b32 v26, v53, s51, v26
	ds_write2_b32 v27, v25, v26 offset0:168 offset1:236
	v_and_b32_e32 v25, 0xffff, v42
	v_lshrrev_b32_e32 v26, 16, v42
	v_lshl_or_b32 v25, v54, 16, v25
	v_and_or_b32 v26, v54, s51, v26
	v_add_u32_e32 v24, 0x9400, v24
	ds_write2_b32 v24, v25, v26 offset0:48 offset1:116
	v_and_b32_e32 v25, 0xffff, v43
	v_lshrrev_b32_e32 v26, 16, v43
	v_lshl_or_b32 v25, v55, 16, v25
	v_and_or_b32 v26, v55, s51, v26
	ds_write2_b32 v24, v25, v26 offset0:184 offset1:252
	v_mov_b32_e32 v24, v184
	v_mov_b32_e32 v25, v185
	v_mov_b32_e32 v26, v186
	v_mov_b32_e32 v27, v187
	v_mov_b32_e32 v28, v188
	v_mov_b32_e32 v29, v189
	v_mov_b32_e32 v30, v190
	v_mov_b32_e32 v31, v191
	v_mov_b32_e32 v32, v192
; __device__ __forceinline__ void ret_out(const bf16_t* proj, const float* cosT, const float* sinT, const float* decay, const float* gn_g, const float* gn_b,
;                         const bf16_t* states, bf16_t* mix, unsigned char* lds, int tid, int bx) {
;     ...
;             { const unsigned t0w[8] = {vv[0].x, vv[0].y, vv[0].z, vv[0].w, vv[1].x, vv[1].y, vv[1].z, vv[1].w}, t1w[8] = {vv[2].x, vv[2].y, vv[2].z, vv[2].w, vv[3].x, vv[3].y, vv[3].z, vv[3].w};
;               unsigned* V32 = (unsigned*)(Vl + (16 * p8v) * LP + (c0v ^ ((p8v & 3) << 4)));
; #pragma unroll
;               for (int j = 0; j < 16; ++j) { const unsigned x0 = (j & 1) ? (t0w[j >> 1] >> 16) : (t0w[j >> 1] & 0xffffu), x1 = (j & 1) ? (t1w[j >> 1] & 0xffff0000u) : (t1w[j >> 1] << 16);
;                   V32[j * (LP / 2)] = x0 | x1; } }
;         }
;         asm volatile("s_waitcnt vmcnt(0)" ::: "memory");
;         __syncthreads();
;         u32x2 gwv[8];
;         { const bf16_t* gp0 = proj + rowq + 2304 + h * 128 + 4 * fq;
; #pragma unroll
;           for (int e8 = 0; e8 < 8; ++e8) gwv[e8] = *(const u32x2*)(gp0 + 16 * e8); }
	v_mov_b32_e32 v33, v193
	v_mov_b32_e32 v34, v194
	v_mov_b32_e32 v35, v195
	v_mov_b32_e32 v36, v196
	v_mov_b32_e32 v37, v197
	v_mov_b32_e32 v38, v198
	v_mov_b32_e32 v39, v199
	v_lshlrev_b32_e32 v44, 16, v4
	v_and_b32_e32 v45, 0xffff0000, v4
	v_lshl_add_u64 v[40:41], v[16:17], 0, v[154:155]
	v_lshlrev_b32_e32 v16, 16, v0
	v_and_b32_e32 v17, 0xffff0000, v0
	v_lshl_add_u64 v[42:43], v[40:41], 0, s[0:1]
	s_movk_i32 s0, 0x1000
	v_mul_f32_e32 v63, 0x3fb8aa3b, v23
	v_sub_u32_e32 v53, v86, v154
	v_pk_mul_f32 v[46:47], v[36:37], v[44:45]
	s_nop 0
	v_pk_fma_f32 v[46:47], v[28:29], v[16:17], v[46:47] neg_lo:[0,0,1] neg_hi:[0,0,1]
	v_pk_mul_f32 v[16:17], v[36:37], v[16:17]
	v_cvt_pk_bf16_f32 v4, v46, v47
	v_pk_fma_f32 v[16:17], v[28:29], v[44:45], v[16:17]
	v_lshlrev_b32_e32 v28, 16, v5
	v_and_b32_e32 v29, 0xffff0000, v5
	v_cvt_pk_bf16_f32 v0, v16, v17
	v_lshlrev_b32_e32 v16, 16, v1
	v_and_b32_e32 v17, 0xffff0000, v1
	v_pk_mul_f32 v[36:37], v[38:39], v[28:29]
	s_nop 0
	v_pk_fma_f32 v[36:37], v[30:31], v[16:17], v[36:37] neg_lo:[0,0,1] neg_hi:[0,0,1]
	v_pk_mul_f32 v[16:17], v[38:39], v[16:17]
	v_cvt_pk_bf16_f32 v5, v36, v37
	v_pk_fma_f32 v[16:17], v[30:31], v[28:29], v[16:17]
	v_lshlrev_b32_e32 v28, 16, v6
	v_and_b32_e32 v29, 0xffff0000, v6
	v_cvt_pk_bf16_f32 v1, v16, v17
	v_lshlrev_b32_e32 v16, 16, v2
	v_and_b32_e32 v17, 0xffff0000, v2
	v_pk_mul_f32 v[30:31], v[32:33], v[28:29]
	v_lshlrev_b32_e32 v36, 16, v12
	v_pk_fma_f32 v[30:31], v[24:25], v[16:17], v[30:31] neg_lo:[0,0,1] neg_hi:[0,0,1]
	v_pk_mul_f32 v[16:17], v[32:33], v[16:17]
	v_cvt_pk_bf16_f32 v6, v30, v31
	v_pk_fma_f32 v[16:17], v[24:25], v[28:29], v[16:17]
	v_lshlrev_b32_e32 v24, 16, v7
	v_and_b32_e32 v25, 0xffff0000, v7
	v_cvt_pk_bf16_f32 v2, v16, v17
	v_lshlrev_b32_e32 v16, 16, v3
	v_and_b32_e32 v17, 0xffff0000, v3
	v_pk_mul_f32 v[28:29], v[34:35], v[24:25]
	v_and_b32_e32 v37, 0xffff0000, v12
	v_pk_fma_f32 v[28:29], v[26:27], v[16:17], v[28:29] neg_lo:[0,0,1] neg_hi:[0,0,1]
	v_pk_mul_f32 v[16:17], v[34:35], v[16:17]
	v_cvt_pk_bf16_f32 v7, v28, v29
	v_pk_fma_f32 v[16:17], v[26:27], v[24:25], v[16:17]
	s_nop 0
	v_cvt_pk_bf16_f32 v3, v16, v17
	v_mov_b32_e32 v24, v200
	v_mov_b32_e32 v25, v201
	v_mov_b32_e32 v26, v202
	v_mov_b32_e32 v27, v203
	v_mov_b32_e32 v16, v204
	v_mov_b32_e32 v17, v205
	v_mov_b32_e32 v18, v206
	v_mov_b32_e32 v19, v207
	v_mov_b32_e32 v28, v208
	v_mov_b32_e32 v29, v209
	v_mov_b32_e32 v30, v210
	v_mov_b32_e32 v31, v211
	v_mov_b32_e32 v32, v212
	v_mov_b32_e32 v33, v213
	v_mov_b32_e32 v34, v214
	v_mov_b32_e32 v35, v215
	v_lshlrev_b32_e32 v20, 16, v8
	v_and_b32_e32 v21, 0xffff0000, v8
	s_waitcnt vmcnt(0)
	s_waitcnt lgkmcnt(0)
	s_barrier
	s_waitcnt vmcnt(0)
	v_pk_mul_f32 v[38:39], v[32:33], v[36:37]
	s_nop 0
	v_pk_fma_f32 v[38:39], v[16:17], v[20:21], v[38:39] neg_lo:[0,0,1] neg_hi:[0,0,1]
	v_pk_mul_f32 v[20:21], v[32:33], v[20:21]
	v_cvt_pk_bf16_f32 v12, v38, v39
	v_pk_fma_f32 v[16:17], v[16:17], v[36:37], v[20:21]
	v_lshlrev_b32_e32 v20, 16, v13
	v_and_b32_e32 v21, 0xffff0000, v13
	v_cvt_pk_bf16_f32 v8, v16, v17
	v_lshlrev_b32_e32 v16, 16, v9
	v_and_b32_e32 v17, 0xffff0000, v9
	v_pk_mul_f32 v[32:33], v[34:35], v[20:21]
	s_nop 0
	v_pk_fma_f32 v[32:33], v[18:19], v[16:17], v[32:33] neg_lo:[0,0,1] neg_hi:[0,0,1]
	v_pk_mul_f32 v[16:17], v[34:35], v[16:17]
	v_cvt_pk_bf16_f32 v13, v32, v33
	v_pk_fma_f32 v[16:17], v[18:19], v[20:21], v[16:17]
	v_lshlrev_b32_e32 v18, 16, v14
	v_and_b32_e32 v19, 0xffff0000, v14
	v_cvt_pk_bf16_f32 v9, v16, v17
	v_lshlrev_b32_e32 v16, 16, v10
	v_and_b32_e32 v17, 0xffff0000, v10
	v_pk_mul_f32 v[20:21], v[28:29], v[18:19]
	s_nop 0
	v_pk_fma_f32 v[20:21], v[24:25], v[16:17], v[20:21] neg_lo:[0,0,1] neg_hi:[0,0,1]
	v_pk_mul_f32 v[16:17], v[28:29], v[16:17]
	v_cvt_pk_bf16_f32 v14, v20, v21
	v_pk_fma_f32 v[16:17], v[24:25], v[18:19], v[16:17]
	v_lshlrev_b32_e32 v18, 16, v15
	v_cvt_pk_bf16_f32 v10, v16, v17
	v_add_co_u32_e32 v16, vcc, s0, v40
	v_and_b32_e32 v19, 0xffff0000, v15
	s_nop 0
	v_addc_co_u32_e32 v17, vcc, 0, v41, vcc
	global_load_dwordx2 v[78:79], v[16:17], off offset:512
	global_load_dwordx2 v[76:77], v[42:43], off offset:32
	global_load_dwordx2 v[74:75], v[42:43], off offset:64
	global_load_dwordx2 v[72:73], v[42:43], off offset:96
	global_load_dwordx2 v[70:71], v[42:43], off offset:128
	global_load_dwordx2 v[68:69], v[42:43], off offset:160
	global_load_dwordx2 v[66:67], v[42:43], off offset:192
	global_load_dwordx2 v[64:65], v[42:43], off offset:224
	v_lshlrev_b32_e32 v16, 16, v11
	v_and_b32_e32 v17, 0xffff0000, v11
	v_pk_mul_f32 v[20:21], v[30:31], v[18:19]
	s_movk_i32 s0, 0x58
	v_pk_fma_f32 v[20:21], v[26:27], v[16:17], v[20:21] neg_lo:[0,0,1] neg_hi:[0,0,1]
	v_pk_mul_f32 v[16:17], v[30:31], v[16:17]
	v_cvt_pk_bf16_f32 v15, v20, v21
	v_pk_fma_f32 v[16:17], v[26:27], v[18:19], v[16:17]
	s_waitcnt vmcnt(2)
	s_cmpk_gt_i32 s49, 0x5ff
	s_cbranch_scc1 .Lro_nopf
	s_lshr_b32 s14, s49, 5
	s_and_b32 s15, s49, 31
	s_mul_hi_u32 s17, s14, 0x2aaaaaab
	s_mul_i32 s18, s17, 6
	s_sub_i32 s18, s14, s18
	s_lshl_b32 s100, s14, 21
	s_lshl_b32 s101, s15, 15
	s_add_u32 s100, s100, s101
	s_add_u32 s100, s24, s100
	s_addc_u32 s101, s25, 0
	v_lshlrev_b32_e32 v216, 6, v173
	v_lshrrev_b32_e32 v217, 2, v173
	global_load_dword v218, v216, s[100:101]
	s_add_u32 s100, s100, 0x100000
	s_addc_u32 s101, s101, 0
	v_mul_u32_u24_e32 v217, 0x1a00, v217
	global_load_dword v218, v216, s[100:101]
	s_lshl_b32 s17, s17, 12
	s_lshl_b32 s15, s15, 7
	s_add_i32 s17, s17, s15
	s_mul_i32 s15, s17, 0x1a00
	s_lshl_b32 s18, s18, 8
	s_add_u32 s15, s15, s18
	s_add_u32 s100, s22, s15
	s_addc_u32 s101, s23, 0
	v_and_b32_e32 v216, 3, v173
	v_lshl_add_u32 v217, v216, 6, v217
	global_load_dword v218, v217, s[100:101]
	global_load_dword v218, v217, s[100:101] offset:1536
	global_load_dword v218, v217, s[100:101] offset:3072
	s_add_u32 s100, s100, 0x1200
	s_addc_u32 s101, s101, 0
	global_load_dword v218, v217, s[100:101]
; __device__ __forceinline__ void ret_out(const bf16_t* proj, const float* cosT, const float* sinT, const float* decay, const float* gn_g, const float* gn_b,
;                         const bf16_t* states, bf16_t* mix, unsigned char* lds, int tid, int bx) {
;     ...
;         bf16x8 pf[4];
; #pragma unroll
;         for (int s = 0; s < 4; ++s) {
;             f32x4 st2[2];
; #pragma unroll
;             for (int pp = 0; pp < 2; ++pp) {
;                 const bf16_t* kr = Kl + (32 * s + 8 * (fr >> 2) + 4 * pp + (fr & 3)) * LP + 8 * fq;
;                 f32x4 a = (f32x4){0.f, 0.f, 0.f, 0.f};
; #pragma unroll
;                 for (int ks = 0; ks < 4; ++ks) a = __builtin_amdgcn_mfma_f32_16x16x32_bf16(*(const bf16x8*)(kr + 32 * ks), qf[ks], a, 0, 0, 0);
; #pragma unroll
;                 for (int r = 0; r < 4; ++r) { const int sk = 32 * s + 8 * fq + 4 * pp + r, diff = cq - sk;
;                     const float df = (float)diff;
;                     const float dd = __builtin_amdgcn_exp2f(fminf(lgf2 * df, -lgb2 * df)) + fmaxf(1.0f - fabsf(df), 0.0f);
;                     a[r] *= dd * 0.08838834764831845f; }
;                 st2[pp] = a;
;             }
;             const u32x4 pw = (u32x4){cvt_pk_bf16(st2[0][0], st2[0][1]), cvt_pk_bf16(st2[0][2], st2[0][3]), cvt_pk_bf16(st2[1][0], st2[1][1]), cvt_pk_bf16(st2[1][2], st2[1][3])};
;             __builtin_memcpy(&pf[s], &pw, 16);
;         }
.Lro_nopf:
	v_lshlrev_b32_e32 v142, 16, v69
	v_cvt_pk_bf16_f32 v11, v16, v17
	v_lshlrev_b32_e32 v16, 1, v22
	v_and_b32_e32 v17, 3, v22
	v_and_or_b32 v16, v16, 24, v17
	v_mul_u32_u24_e32 v16, 0x110, v16
	v_add3_u32 v52, 0, v62, v16
	ds_read_b128 v[16:19], v52
	ds_read_b128 v[20:23], v52 offset:64
	s_waitcnt lgkmcnt(1)
	v_mfma_f32_16x16x32_bf16 v[16:19], v[16:19], v[4:7], 0
	ds_read_b128 v[24:27], v52 offset:1152
	v_and_b32_e32 v143, 0xffff0000, v69
	v_lshlrev_b32_e32 v146, 16, v68
	s_waitcnt lgkmcnt(1)
	v_mfma_f32_16x16x32_bf16 v[16:19], v[20:23], v[12:15], v[16:19]
	ds_read_b128 v[20:23], v52 offset:128
	v_and_b32_e32 v147, 0xffff0000, v68
	s_waitcnt lgkmcnt(0)
	v_mfma_f32_16x16x32_bf16 v[16:19], v[20:23], v[0:3], v[16:19]
	ds_read_b128 v[20:23], v52 offset:192
	s_waitcnt lgkmcnt(0)
	v_mfma_f32_16x16x32_bf16 v[16:19], v[20:23], v[8:11], v[16:19]
	v_cvt_f32_i32_e32 v20, v53
	v_mul_f32_e32 v21, v87, v20
	v_mul_f32_e32 v22, v63, v20
	v_sub_f32_e64 v20, 1.0, |v20|
	v_max_f32_e32 v30, 0, v20
	v_xad_u32 v20, v154, -1, v86
	v_cvt_f32_i32_e32 v20, v20
	v_min_f32_e32 v21, v21, v22
	v_exp_f32_e32 v28, v21
	v_mul_f32_e32 v21, v87, v20
	v_mul_f32_e32 v22, v63, v20
	v_sub_f32_e64 v20, 1.0, |v20|
	v_max_f32_e32 v31, 0, v20
	v_add_u32_e32 v20, -2, v53
	v_cvt_f32_i32_e32 v20, v20
	v_min_f32_e32 v21, v21, v22
	v_exp_f32_e32 v29, v21
	v_mul_f32_e32 v21, v87, v20
	v_mul_f32_e32 v22, v63, v20
	v_sub_f32_e64 v20, 1.0, |v20|
	v_max_f32_e32 v34, 0, v20
	v_add_u32_e32 v20, -3, v53
	v_cvt_f32_i32_e32 v20, v20
	v_min_f32_e32 v21, v21, v22
	v_exp_f32_e32 v32, v21
	v_pk_add_f32 v[28:29], v[28:29], v[30:31]
	v_mul_f32_e32 v21, v87, v20
	v_mul_f32_e32 v22, v63, v20
	v_min_f32_e32 v21, v21, v22
	v_sub_f32_e64 v20, 1.0, |v20|
	v_exp_f32_e32 v33, v21
	v_max_f32_e32 v35, 0, v20
	ds_read_b128 v[20:23], v52 offset:1088
	s_waitcnt lgkmcnt(0)
	v_mfma_f32_16x16x32_bf16 v[20:23], v[20:23], v[4:7], 0
	v_mul_f32_e64 v28, v28, s54
	v_mul_f32_e64 v29, v29, s54
	v_pk_mul_f32 v[16:17], v[28:29], v[16:17]
	v_mfma_f32_16x16x32_bf16 v[20:23], v[24:27], v[12:15], v[20:23]
	ds_read_b128 v[24:27], v52 offset:1216
	v_pk_add_f32 v[28:29], v[32:33], v[34:35]
	v_cvt_pk_bf16_f32 v16, v16, v17
	s_waitcnt lgkmcnt(0)
	v_mfma_f32_16x16x32_bf16 v[20:23], v[24:27], v[0:3], v[20:23]
	ds_read_b128 v[24:27], v52 offset:1280
	v_pk_mul_f32 v[28:29], v[28:29], s[54:55] op_sel_hi:[1,0]
	s_waitcnt lgkmcnt(0)
	v_mfma_f32_16x16x32_bf16 v[20:23], v[24:27], v[8:11], v[20:23]
	v_add_u32_e32 v24, -4, v53
	v_cvt_f32_i32_e32 v25, v24
	v_pk_mul_f32 v[18:19], v[28:29], v[18:19]
	v_or_b32_e32 v28, 32, v154
	v_cvt_pk_bf16_f32 v17, v18, v19
	v_mul_f32_e32 v24, v87, v25
	v_mul_f32_e32 v26, v63, v25
	v_sub_f32_e64 v25, 1.0, |v25|
	v_min_f32_e32 v24, v24, v26
	v_max_f32_e32 v26, 0, v25
	v_add_u32_e32 v25, -5, v53
	v_cvt_f32_i32_e32 v27, v25
	v_exp_f32_e32 v24, v24
	v_mul_f32_e32 v25, v87, v27
	v_mul_f32_e32 v36, v63, v27
	v_min_f32_e32 v25, v25, v36
	v_add_u32_e32 v36, -6, v53
	v_cvt_f32_i32_e32 v37, v36
	v_exp_f32_e32 v25, v25
	v_sub_f32_e64 v27, 1.0, |v27|
	v_max_f32_e32 v27, 0, v27
	v_mul_f32_e32 v36, v87, v37
	v_mul_f32_e32 v38, v63, v37
	v_sub_f32_e64 v37, 1.0, |v37|
	v_min_f32_e32 v36, v36, v38
	v_max_f32_e32 v38, 0, v37
	v_add_u32_e32 v37, -7, v53
	v_cvt_f32_i32_e32 v39, v37
	v_exp_f32_e32 v36, v36
	v_pk_add_f32 v[18:19], v[24:25], v[26:27]
	ds_read_b128 v[24:27], v52 offset:8768
	v_mul_f32_e32 v37, v87, v39
	v_mul_f32_e32 v40, v63, v39
	v_min_f32_e32 v37, v37, v40
	v_exp_f32_e32 v37, v37
	v_sub_f32_e64 v39, 1.0, |v39|
	v_max_f32_e32 v39, 0, v39
	v_pk_mul_f32 v[18:19], v[18:19], s[54:55] op_sel_hi:[1,0]
	s_nop 0
	v_pk_mul_f32 v[18:19], v[18:19], v[20:21]
	v_pk_add_f32 v[20:21], v[36:37], v[38:39]
	v_cvt_pk_bf16_f32 v18, v18, v19
	v_pk_mul_f32 v[20:21], v[20:21], s[54:55] op_sel_hi:[1,0]
	s_nop 0
	v_pk_mul_f32 v[20:21], v[20:21], v[22:23]
	s_nop 0
	v_cvt_pk_bf16_f32 v19, v20, v21
	ds_read_b128 v[20:23], v52 offset:8704
	s_waitcnt lgkmcnt(0)
	v_mfma_f32_16x16x32_bf16 v[20:23], v[20:23], v[4:7], 0
	v_mfma_f32_16x16x32_bf16 v[20:23], v[24:27], v[12:15], v[20:23]
	ds_read_b128 v[24:27], v52 offset:8832
	s_waitcnt lgkmcnt(0)
	v_mfma_f32_16x16x32_bf16 v[20:23], v[24:27], v[0:3], v[20:23]
	ds_read_b128 v[24:27], v52 offset:8896
	s_waitcnt lgkmcnt(0)
	v_mfma_f32_16x16x32_bf16 v[20:23], v[24:27], v[8:11], v[20:23]
	v_sub_u32_e32 v24, v86, v28
	v_cvt_f32_i32_e32 v24, v24
	ds_read_b128 v[28:31], v52 offset:9856
	v_mul_f32_e32 v25, v87, v24
	v_mul_f32_e32 v26, v63, v24
	v_sub_f32_e64 v24, 1.0, |v24|
	v_max_f32_e32 v34, 0, v24
	v_subrev_u32_e32 v24, 33, v53
	v_cvt_f32_i32_e32 v24, v24
	v_min_f32_e32 v25, v25, v26
	v_exp_f32_e32 v32, v25
	v_mul_f32_e32 v25, v87, v24
	v_mul_f32_e32 v26, v63, v24
	v_sub_f32_e64 v24, 1.0, |v24|
	v_max_f32_e32 v35, 0, v24
	v_subrev_u32_e32 v24, 34, v53
	v_cvt_f32_i32_e32 v24, v24
	v_min_f32_e32 v25, v25, v26
	v_exp_f32_e32 v33, v25
	v_mul_f32_e32 v25, v87, v24
	v_mul_f32_e32 v26, v63, v24
	v_sub_f32_e64 v24, 1.0, |v24|
	v_max_f32_e32 v38, 0, v24
	v_subrev_u32_e32 v24, 35, v53
	v_cvt_f32_i32_e32 v24, v24
	v_min_f32_e32 v25, v25, v26
	v_exp_f32_e32 v36, v25
	v_pk_add_f32 v[32:33], v[32:33], v[34:35]
	v_mul_f32_e32 v25, v87, v24
	v_mul_f32_e32 v26, v63, v24
	v_min_f32_e32 v25, v25, v26
	v_sub_f32_e64 v24, 1.0, |v24|
	v_exp_f32_e32 v37, v25
	v_max_f32_e32 v39, 0, v24
	ds_read_b128 v[24:27], v52 offset:9792
	s_waitcnt lgkmcnt(0)
	v_mfma_f32_16x16x32_bf16 v[24:27], v[24:27], v[4:7], 0
	v_mul_f32_e64 v32, v32, s54
	v_mul_f32_e64 v33, v33, s54
	v_pk_mul_f32 v[20:21], v[32:33], v[20:21]
	v_mfma_f32_16x16x32_bf16 v[24:27], v[28:31], v[12:15], v[24:27]
	ds_read_b128 v[28:31], v52 offset:9920
	v_pk_add_f32 v[32:33], v[36:37], v[38:39]
	v_cvt_pk_bf16_f32 v20, v20, v21
	s_waitcnt lgkmcnt(0)
; __device__ __forceinline__ void ret_out(const bf16_t* proj, const float* cosT, const float* sinT, const float* decay, const float* gn_g, const float* gn_b,
;                         const bf16_t* states, bf16_t* mix, unsigned char* lds, int tid, int bx) {
;     ...
;         for (int s = 0; s < 4; ++s) {
;             f32x4 st2[2];
; #pragma unroll
;             for (int pp = 0; pp < 2; ++pp) {
;                 const bf16_t* kr = Kl + (32 * s + 8 * (fr >> 2) + 4 * pp + (fr & 3)) * LP + 8 * fq;
;                 f32x4 a = (f32x4){0.f, 0.f, 0.f, 0.f};
; #pragma unroll
;                 for (int ks = 0; ks < 4; ++ks) a = __builtin_amdgcn_mfma_f32_16x16x32_bf16(*(const bf16x8*)(kr + 32 * ks), qf[ks], a, 0, 0, 0);
; #pragma unroll
;                 for (int r = 0; r < 4; ++r) { const int sk = 32 * s + 8 * fq + 4 * pp + r, diff = cq - sk;
;                     const float df = (float)diff;
;                     const float dd = __builtin_amdgcn_exp2f(fminf(lgf2 * df, -lgb2 * df)) + fmaxf(1.0f - fabsf(df), 0.0f);
;                     a[r] *= dd * 0.08838834764831845f; }
;                 st2[pp] = a;
;             }
;             const u32x4 pw = (u32x4){cvt_pk_bf16(st2[0][0], st2[0][1]), cvt_pk_bf16(st2[0][2], st2[0][3]), cvt_pk_bf16(st2[1][0], st2[1][1]), cvt_pk_bf16(st2[1][2], st2[1][3])};
;             __builtin_memcpy(&pf[s], &pw, 16);
;         }
	v_mfma_f32_16x16x32_bf16 v[24:27], v[28:31], v[0:3], v[24:27]
	ds_read_b128 v[28:31], v52 offset:9984
	v_pk_mul_f32 v[32:33], v[32:33], s[54:55] op_sel_hi:[1,0]
	s_waitcnt lgkmcnt(0)
	v_mfma_f32_16x16x32_bf16 v[24:27], v[28:31], v[8:11], v[24:27]
	v_subrev_u32_e32 v28, 36, v53
	v_cvt_f32_i32_e32 v29, v28
	v_pk_mul_f32 v[22:23], v[32:33], v[22:23]
	v_or_b32_e32 v32, 64, v154
	v_cvt_pk_bf16_f32 v21, v22, v23
	v_mul_f32_e32 v28, v87, v29
	v_mul_f32_e32 v30, v63, v29
	v_sub_f32_e64 v29, 1.0, |v29|
	v_min_f32_e32 v28, v28, v30
	v_max_f32_e32 v30, 0, v29
	v_subrev_u32_e32 v29, 37, v53
	v_cvt_f32_i32_e32 v31, v29
	v_exp_f32_e32 v28, v28
	v_mul_f32_e32 v29, v87, v31
	v_mul_f32_e32 v40, v63, v31
	v_min_f32_e32 v29, v29, v40
	v_subrev_u32_e32 v40, 38, v53
	v_cvt_f32_i32_e32 v41, v40
	v_exp_f32_e32 v29, v29
	v_sub_f32_e64 v31, 1.0, |v31|
	v_max_f32_e32 v31, 0, v31
	v_mul_f32_e32 v40, v87, v41
	v_mul_f32_e32 v42, v63, v41
	v_sub_f32_e64 v41, 1.0, |v41|
	v_min_f32_e32 v40, v40, v42
	v_max_f32_e32 v42, 0, v41
	v_subrev_u32_e32 v41, 39, v53
	v_cvt_f32_i32_e32 v43, v41
	v_exp_f32_e32 v40, v40
	v_pk_add_f32 v[22:23], v[28:29], v[30:31]
	ds_read_b128 v[28:31], v52 offset:17472
	v_mul_f32_e32 v41, v87, v43
	v_mul_f32_e32 v44, v63, v43
	v_min_f32_e32 v41, v41, v44
	v_exp_f32_e32 v41, v41
	v_sub_f32_e64 v43, 1.0, |v43|
	v_max_f32_e32 v43, 0, v43
	v_pk_mul_f32 v[22:23], v[22:23], s[54:55] op_sel_hi:[1,0]
	s_nop 0
	v_pk_mul_f32 v[22:23], v[22:23], v[24:25]
	v_pk_add_f32 v[24:25], v[40:41], v[42:43]
	v_cvt_pk_bf16_f32 v22, v22, v23
	v_pk_mul_f32 v[24:25], v[24:25], s[54:55] op_sel_hi:[1,0]
	s_nop 0
	v_pk_mul_f32 v[24:25], v[24:25], v[26:27]
	s_nop 0
	v_cvt_pk_bf16_f32 v23, v24, v25
	ds_read_b128 v[24:27], v52 offset:17408
	s_waitcnt lgkmcnt(0)
	v_mfma_f32_16x16x32_bf16 v[24:27], v[24:27], v[4:7], 0
	v_mfma_f32_16x16x32_bf16 v[24:27], v[28:31], v[12:15], v[24:27]
	ds_read_b128 v[28:31], v52 offset:17536
	s_waitcnt lgkmcnt(0)
	v_mfma_f32_16x16x32_bf16 v[24:27], v[28:31], v[0:3], v[24:27]
	ds_read_b128 v[28:31], v52 offset:17600
	s_waitcnt lgkmcnt(0)
	v_mfma_f32_16x16x32_bf16 v[24:27], v[28:31], v[8:11], v[24:27]
	v_sub_u32_e32 v28, v86, v32
	v_cvt_f32_i32_e32 v28, v28
	ds_read_b128 v[32:35], v52 offset:18560
	v_mul_f32_e32 v29, v87, v28
	v_mul_f32_e32 v30, v63, v28
	v_sub_f32_e64 v28, 1.0, |v28|
	v_max_f32_e32 v38, 0, v28
	v_add_u32_e32 v28, 0xffffffbf, v53
	v_cvt_f32_i32_e32 v28, v28
	v_min_f32_e32 v29, v29, v30
	v_exp_f32_e32 v36, v29
	v_mul_f32_e32 v29, v87, v28
	v_mul_f32_e32 v30, v63, v28
	v_sub_f32_e64 v28, 1.0, |v28|
	v_max_f32_e32 v39, 0, v28
	v_add_u32_e32 v28, 0xffffffbe, v53
	v_cvt_f32_i32_e32 v28, v28
	v_min_f32_e32 v29, v29, v30
	v_exp_f32_e32 v37, v29
	v_mul_f32_e32 v29, v87, v28
	v_mul_f32_e32 v30, v63, v28
	v_sub_f32_e64 v28, 1.0, |v28|
	v_max_f32_e32 v42, 0, v28
	v_add_u32_e32 v28, 0xffffffbd, v53
	v_cvt_f32_i32_e32 v28, v28
	v_min_f32_e32 v29, v29, v30
	v_exp_f32_e32 v40, v29
	v_pk_add_f32 v[36:37], v[36:37], v[38:39]
	v_mul_f32_e32 v29, v87, v28
	v_mul_f32_e32 v30, v63, v28
	v_min_f32_e32 v29, v29, v30
	v_sub_f32_e64 v28, 1.0, |v28|
	v_exp_f32_e32 v41, v29
	v_max_f32_e32 v43, 0, v28
	ds_read_b128 v[28:31], v52 offset:18496
	s_waitcnt lgkmcnt(0)
	v_mfma_f32_16x16x32_bf16 v[28:31], v[28:31], v[4:7], 0
	v_mul_f32_e64 v36, v36, s54
	v_mul_f32_e64 v37, v37, s54
	v_pk_mul_f32 v[24:25], v[36:37], v[24:25]
	v_mfma_f32_16x16x32_bf16 v[28:31], v[32:35], v[12:15], v[28:31]
	ds_read_b128 v[32:35], v52 offset:18624
	s_waitcnt lgkmcnt(0)
	v_mfma_f32_16x16x32_bf16 v[28:31], v[32:35], v[0:3], v[28:31]
	ds_read_b128 v[32:35], v52 offset:18688
	s_waitcnt lgkmcnt(0)
	v_mfma_f32_16x16x32_bf16 v[28:31], v[32:35], v[8:11], v[28:31]
	v_add_u32_e32 v32, 0xffffffbc, v53
	v_cvt_f32_i32_e32 v33, v32
	v_mul_f32_e32 v32, v87, v33
	v_mul_f32_e32 v34, v63, v33
	v_sub_f32_e64 v33, 1.0, |v33|
	v_min_f32_e32 v32, v32, v34
	v_max_f32_e32 v34, 0, v33
	v_add_u32_e32 v33, 0xffffffbb, v53
	v_cvt_f32_i32_e32 v35, v33
	v_exp_f32_e32 v32, v32
	v_mul_f32_e32 v33, v87, v35
	v_mul_f32_e32 v44, v63, v35
	v_min_f32_e32 v33, v33, v44
	v_add_u32_e32 v44, 0xffffffba, v53
	v_cvt_f32_i32_e32 v45, v44
	v_exp_f32_e32 v33, v33
	v_sub_f32_e64 v35, 1.0, |v35|
	v_max_f32_e32 v35, 0, v35
	v_mul_f32_e32 v44, v87, v45
	v_mul_f32_e32 v46, v63, v45
	v_sub_f32_e64 v45, 1.0, |v45|
	v_min_f32_e32 v44, v44, v46
	v_max_f32_e32 v46, 0, v45
	v_add_u32_e32 v45, 0xffffffb9, v53
	v_cvt_f32_i32_e32 v47, v45
	v_exp_f32_e32 v44, v44
	v_mul_f32_e32 v45, v87, v47
	v_mul_f32_e32 v48, v63, v47
	v_min_f32_e32 v45, v45, v48
	v_cvt_pk_bf16_f32 v48, v24, v25
	v_pk_add_f32 v[24:25], v[40:41], v[42:43]
	v_exp_f32_e32 v45, v45
	v_pk_mul_f32 v[24:25], v[24:25], s[54:55] op_sel_hi:[1,0]
	v_sub_f32_e64 v47, 1.0, |v47|
	v_pk_mul_f32 v[24:25], v[24:25], v[26:27]
	v_max_f32_e32 v47, 0, v47
	v_cvt_pk_bf16_f32 v49, v24, v25
	v_pk_add_f32 v[24:25], v[32:33], v[34:35]
	v_or_b32_e32 v32, 0x60, v154
	v_pk_mul_f32 v[24:25], v[24:25], s[54:55] op_sel_hi:[1,0]
	s_nop 0
	v_pk_mul_f32 v[24:25], v[24:25], v[28:29]
	s_nop 0
	v_cvt_pk_bf16_f32 v50, v24, v25
	v_pk_add_f32 v[24:25], v[44:45], v[46:47]
	s_nop 0
	v_pk_mul_f32 v[24:25], v[24:25], s[54:55] op_sel_hi:[1,0]
	s_nop 0
	v_pk_mul_f32 v[24:25], v[24:25], v[30:31]
	ds_read_b128 v[28:31], v52 offset:26176
	v_cvt_pk_bf16_f32 v51, v24, v25
	ds_read_b128 v[24:27], v52 offset:26112
	s_waitcnt lgkmcnt(0)
	v_mfma_f32_16x16x32_bf16 v[24:27], v[24:27], v[4:7], 0
	v_mfma_f32_16x16x32_bf16 v[24:27], v[28:31], v[12:15], v[24:27]
	ds_read_b128 v[28:31], v52 offset:26240
	s_waitcnt lgkmcnt(0)
	v_mfma_f32_16x16x32_bf16 v[24:27], v[28:31], v[0:3], v[24:27]
	ds_read_b128 v[28:31], v52 offset:26304
	s_waitcnt lgkmcnt(0)
; __device__ __forceinline__ void ret_out(const bf16_t* proj, const float* cosT, const float* sinT, const float* decay, const float* gn_g, const float* gn_b,
;                         const bf16_t* states, bf16_t* mix, unsigned char* lds, int tid, int bx) {
;     ...
;         for (int s = 0; s < 4; ++s) {
;             f32x4 st2[2];
; #pragma unroll
;             for (int pp = 0; pp < 2; ++pp) {
;                 const bf16_t* kr = Kl + (32 * s + 8 * (fr >> 2) + 4 * pp + (fr & 3)) * LP + 8 * fq;
;                 f32x4 a = (f32x4){0.f, 0.f, 0.f, 0.f};
; #pragma unroll
;                 for (int ks = 0; ks < 4; ++ks) a = __builtin_amdgcn_mfma_f32_16x16x32_bf16(*(const bf16x8*)(kr + 32 * ks), qf[ks], a, 0, 0, 0);
; #pragma unroll
;                 for (int r = 0; r < 4; ++r) { const int sk = 32 * s + 8 * fq + 4 * pp + r, diff = cq - sk;
;                     const float df = (float)diff;
;                     const float dd = __builtin_amdgcn_exp2f(fminf(lgf2 * df, -lgb2 * df)) + fmaxf(1.0f - fabsf(df), 0.0f);
;                     a[r] *= dd * 0.08838834764831845f; }
;                 st2[pp] = a;
;             }
;             const u32x4 pw = (u32x4){cvt_pk_bf16(st2[0][0], st2[0][1]), cvt_pk_bf16(st2[0][2], st2[0][3]), cvt_pk_bf16(st2[1][0], st2[1][1]), cvt_pk_bf16(st2[1][2], st2[1][3])};
;             __builtin_memcpy(&pf[s], &pw, 16);
;         }
;         f32x4 acc[8];
; #pragma unroll
;         for (int e8 = 0; e8 < 8; ++e8) acc[e8] = (f32x4){0.f, 0.f, 0.f, 0.f};
; #pragma unroll
;         for (int s = 0; s < 4; ++s)
; #pragma unroll
;             for (int e8 = 0; e8 < 8; ++e8) acc[e8] = __builtin_amdgcn_mfma_f32_16x16x32_bf16(*(const bf16x8*)(Vl + (16 * e8 + fr) * LP + ((32 * s + 8 * fq) ^ ((e8 & 3) << 4))), pf[s], acc[e8], 0, 0, 0);
	v_mfma_f32_16x16x32_bf16 v[24:27], v[28:31], v[8:11], v[24:27]
	v_sub_u32_e32 v28, v86, v32
	v_cvt_f32_i32_e32 v28, v28
	ds_read_b128 v[32:35], v52 offset:27264
	v_mul_f32_e32 v29, v87, v28
	v_mul_f32_e32 v30, v63, v28
	v_sub_f32_e64 v28, 1.0, |v28|
	v_max_f32_e32 v38, 0, v28
	v_add_u32_e32 v28, 0xffffff9f, v53
	v_cvt_f32_i32_e32 v28, v28
	v_min_f32_e32 v29, v29, v30
	v_exp_f32_e32 v36, v29
	v_mul_f32_e32 v29, v87, v28
	v_mul_f32_e32 v30, v63, v28
	v_sub_f32_e64 v28, 1.0, |v28|
	v_max_f32_e32 v39, 0, v28
	v_add_u32_e32 v28, 0xffffff9e, v53
	v_cvt_f32_i32_e32 v28, v28
	v_min_f32_e32 v29, v29, v30
	v_exp_f32_e32 v37, v29
	v_mul_f32_e32 v29, v87, v28
	v_mul_f32_e32 v30, v63, v28
	v_sub_f32_e64 v28, 1.0, |v28|
	v_max_f32_e32 v42, 0, v28
	v_add_u32_e32 v28, 0xffffff9d, v53
	v_cvt_f32_i32_e32 v28, v28
	v_min_f32_e32 v29, v29, v30
	v_exp_f32_e32 v40, v29
	v_pk_add_f32 v[36:37], v[36:37], v[38:39]
	v_mul_f32_e32 v29, v87, v28
	v_mul_f32_e32 v30, v63, v28
	v_min_f32_e32 v29, v29, v30
	v_sub_f32_e64 v28, 1.0, |v28|
	v_exp_f32_e32 v41, v29
	v_max_f32_e32 v43, 0, v28
	ds_read_b128 v[28:31], v52 offset:27200
	s_waitcnt lgkmcnt(0)
	v_mfma_f32_16x16x32_bf16 v[28:31], v[28:31], v[4:7], 0
	v_mul_f32_e64 v36, v36, s54
	v_mul_f32_e64 v37, v37, s54
	v_pk_mul_f32 v[24:25], v[36:37], v[24:25]
	v_mfma_f32_16x16x32_bf16 v[28:31], v[32:35], v[12:15], v[28:31]
	ds_read_b128 v[32:35], v52 offset:27328
	v_pk_add_f32 v[36:37], v[40:41], v[42:43]
	v_cvt_pk_bf16_f32 v24, v24, v25
	s_waitcnt lgkmcnt(0)
	v_mfma_f32_16x16x32_bf16 v[28:31], v[32:35], v[0:3], v[28:31]
	ds_read_b128 v[32:35], v52 offset:27392
	v_pk_mul_f32 v[36:37], v[36:37], s[54:55] op_sel_hi:[1,0]
	s_waitcnt lgkmcnt(0)
	v_mfma_f32_16x16x32_bf16 v[28:31], v[32:35], v[8:11], v[28:31]
	v_add_u32_e32 v32, 0xffffff9c, v53
	v_cvt_f32_i32_e32 v33, v32
	v_pk_mul_f32 v[26:27], v[36:37], v[26:27]
	v_mul_f32_e32 v32, v87, v33
	v_mul_f32_e32 v34, v63, v33
	v_sub_f32_e64 v33, 1.0, |v33|
	v_min_f32_e32 v32, v32, v34
	v_max_f32_e32 v34, 0, v33
	v_add_u32_e32 v33, 0xffffff9b, v53
	v_cvt_f32_i32_e32 v35, v33
	v_exp_f32_e32 v32, v32
	v_cvt_pk_bf16_f32 v25, v26, v27
	v_mul_f32_e32 v33, v87, v35
	v_mul_f32_e32 v44, v63, v35
	v_min_f32_e32 v33, v33, v44
	v_add_u32_e32 v44, 0xffffff9a, v53
	v_cvt_f32_i32_e32 v45, v44
	v_exp_f32_e32 v33, v33
	v_sub_f32_e64 v35, 1.0, |v35|
	v_max_f32_e32 v35, 0, v35
	v_mul_f32_e32 v44, v87, v45
	v_mul_f32_e32 v46, v63, v45
	v_sub_f32_e64 v45, 1.0, |v45|
	v_min_f32_e32 v44, v44, v46
	v_max_f32_e32 v46, 0, v45
	v_add_u32_e32 v45, 0xffffff99, v53
	v_cvt_f32_i32_e32 v47, v45
	v_exp_f32_e32 v44, v44
	v_pk_add_f32 v[26:27], v[32:33], v[34:35]
	v_bitop3_b32 v53, v154, s0, v180 bitop3:0xc8
	v_mul_f32_e32 v45, v87, v47
	v_mul_f32_e32 v52, v63, v47
	v_min_f32_e32 v45, v45, v52
	v_exp_f32_e32 v45, v45
	v_sub_f32_e64 v47, 1.0, |v47|
	v_max_f32_e32 v47, 0, v47
	v_pk_mul_f32 v[26:27], v[26:27], s[54:55] op_sel_hi:[1,0]
	v_mad_u32_u24 v52, v83, s52, 0
	v_pk_mul_f32 v[26:27], v[26:27], v[28:29]
	v_pk_add_f32 v[28:29], v[44:45], v[46:47]
	v_add_u32_e32 v89, v52, v62
	v_pk_mul_f32 v[28:29], v[28:29], s[54:55] op_sel_hi:[1,0]
	v_xad_u32 v88, v62, 32, v52
	v_pk_mul_f32 v[28:29], v[28:29], v[30:31]
	v_cvt_pk_bf16_f32 v26, v26, v27
	v_cvt_pk_bf16_f32 v27, v28, v29
	ds_read_b128 v[28:31], v89 offset:34816
	ds_read_b128 v[36:39], v89 offset:43584
	ds_read_b128 v[32:35], v88 offset:39168
	ds_read_b128 v[40:43], v88 offset:47936
	ds_read_b128 v[44:47], v89 offset:52224
	ds_read_b128 v[90:93], v89 offset:60992
	ds_read_b128 v[54:57], v88 offset:56576
	ds_read_b128 v[94:97], v88 offset:65344
	s_waitcnt lgkmcnt(7)
	v_mfma_f32_16x16x32_bf16 v[28:31], v[28:31], v[16:19], 0
	s_lshl_b32 s0, s36, 9
	s_add_i32 s0, s0, 0
	s_cmpk_lt_i32 s49, 0x600
	s_waitcnt lgkmcnt(5)
	v_mfma_f32_16x16x32_bf16 v[32:35], v[32:35], v[16:19], 0
	v_mfma_f32_16x16x32_bf16 v[36:39], v[36:39], v[16:19], 0
	s_waitcnt lgkmcnt(4)
	v_mfma_f32_16x16x32_bf16 v[40:43], v[40:43], v[16:19], 0
	s_waitcnt lgkmcnt(3)
	v_mfma_f32_16x16x32_bf16 v[44:47], v[44:47], v[16:19], 0
	s_waitcnt lgkmcnt(1)
	v_mfma_f32_16x16x32_bf16 v[54:57], v[54:57], v[16:19], 0
	v_mfma_f32_16x16x32_bf16 v[90:93], v[90:93], v[16:19], 0
	s_waitcnt lgkmcnt(0)
	v_mfma_f32_16x16x32_bf16 v[16:19], v[94:97], v[16:19], 0
	ds_read_b128 v[94:97], v89 offset:34880
	s_waitcnt lgkmcnt(0)
	v_mfma_f32_16x16x32_bf16 v[28:31], v[94:97], v[20:23], v[28:31]
	ds_read_b128 v[94:97], v88 offset:39232
	s_waitcnt lgkmcnt(0)
	v_mfma_f32_16x16x32_bf16 v[32:35], v[94:97], v[20:23], v[32:35]
	ds_read_b128 v[94:97], v89 offset:43520
	s_waitcnt lgkmcnt(0)
	v_mfma_f32_16x16x32_bf16 v[36:39], v[94:97], v[20:23], v[36:39]
	ds_read_b128 v[94:97], v88 offset:47872
	s_waitcnt lgkmcnt(0)
	v_mfma_f32_16x16x32_bf16 v[40:43], v[94:97], v[20:23], v[40:43]
	ds_read_b128 v[94:97], v89 offset:52288
	s_waitcnt lgkmcnt(0)
	v_mfma_f32_16x16x32_bf16 v[44:47], v[94:97], v[20:23], v[44:47]
	ds_read_b128 v[94:97], v88 offset:56640
	s_waitcnt lgkmcnt(0)
	v_mfma_f32_16x16x32_bf16 v[54:57], v[94:97], v[20:23], v[54:57]
	ds_read_b128 v[94:97], v89 offset:60928
	s_waitcnt lgkmcnt(0)
	v_mfma_f32_16x16x32_bf16 v[90:93], v[94:97], v[20:23], v[90:93]
	ds_read_b128 v[94:97], v88 offset:65280
	s_waitcnt lgkmcnt(0)
	v_mfma_f32_16x16x32_bf16 v[16:19], v[94:97], v[20:23], v[16:19]
	ds_read_b128 v[20:23], v89 offset:34944
	s_waitcnt lgkmcnt(0)
	v_mfma_f32_16x16x32_bf16 v[20:23], v[20:23], v[48:51], v[28:31]
	s_nop 2
	ds_read_b128 v[28:31], v88 offset:39296
	s_waitcnt lgkmcnt(0)
	v_mfma_f32_16x16x32_bf16 v[94:97], v[28:31], v[48:51], v[32:35]
	ds_read_b128 v[28:31], v89 offset:43712
	s_nop 1
	ds_read_b128 v[32:35], v88 offset:48064
	s_waitcnt lgkmcnt(1)
; __device__ __forceinline__ void ret_out(const bf16_t* proj, const float* cosT, const float* sinT, const float* decay, const float* gn_g, const float* gn_b,
;                         const bf16_t* states, bf16_t* mix, unsigned char* lds, int tid, int bx) {
;     ...
; #pragma unroll
;         for (int s = 0; s < 4; ++s)
; #pragma unroll
;             for (int e8 = 0; e8 < 8; ++e8) acc[e8] = __builtin_amdgcn_mfma_f32_16x16x32_bf16(*(const bf16x8*)(Vl + (16 * e8 + fr) * LP + ((32 * s + 8 * fq) ^ ((e8 & 3) << 4))), pf[s], acc[e8], 0, 0, 0);
; #pragma unroll
;         for (int dir = 0; dir < 2; ++dir) {
;             const unsigned char* sl = lds + ST_OFF + dir * 32768 + fr * 256;
;             const float sc = dir == 0 ? __builtin_amdgcn_exp2f(lgf2 * (float)(cq + 1)) : __builtin_amdgcn_exp2f(lgb2 * (float)(128 - cq));
; #pragma unroll
;             for (int e8 = 0; e8 < 8; ++e8) {
;                 f32x4 a2 = (f32x4){0.f, 0.f, 0.f, 0.f};
; #pragma unroll
;                 for (int ks = 0; ks < 4; ++ks) a2 = __builtin_amdgcn_mfma_f32_16x16x32_bf16(*(const bf16x8*)(sl + e8 * 4096 + (((4 * ks + fq) ^ fr) << 4)), qf[ks], a2, 0, 0, 0);
;                 acc[e8] += a2 * sc;
;             }
;         }
	v_mfma_f32_16x16x32_bf16 v[28:31], v[28:31], v[48:51], v[36:39]
	s_nop 2
	ds_read_b128 v[36:39], v89 offset:52352
	s_waitcnt lgkmcnt(1)
	v_mfma_f32_16x16x32_bf16 v[32:35], v[32:35], v[48:51], v[40:43]
	s_nop 2
	ds_read_b128 v[40:43], v88 offset:56704
	s_waitcnt lgkmcnt(1)
	v_mfma_f32_16x16x32_bf16 v[36:39], v[36:39], v[48:51], v[44:47]
	s_nop 2
	ds_read_b128 v[44:47], v89 offset:61120
	s_waitcnt lgkmcnt(1)
	v_mfma_f32_16x16x32_bf16 v[40:43], v[40:43], v[48:51], v[54:57]
	s_nop 2
	ds_read_b128 v[54:57], v88 offset:65472
	s_waitcnt lgkmcnt(1)
	v_mfma_f32_16x16x32_bf16 v[44:47], v[44:47], v[48:51], v[90:93]
	s_nop 2
	v_lshl_add_u32 v90, v53, 1, v52
	s_waitcnt lgkmcnt(0)
	v_mfma_f32_16x16x32_bf16 v[48:51], v[54:57], v[48:51], v[16:19]
	ds_read_b128 v[52:55], v90 offset:43520
	s_nop 1
	ds_read_b128 v[16:19], v89 offset:35008
	s_waitcnt lgkmcnt(0)
	v_mfma_f32_16x16x32_bf16 v[20:23], v[16:19], v[24:27], v[20:23]
	ds_read_b128 v[16:19], v88 offset:39360
	v_mfma_f32_16x16x32_bf16 v[56:59], v[52:55], v[24:27], v[28:31]
	s_nop 2
	ds_read_b128 v[28:31], v88 offset:48000
	s_waitcnt lgkmcnt(0)
	v_mfma_f32_16x16x32_bf16 v[52:55], v[28:31], v[24:27], v[32:35]
	ds_read_b128 v[28:31], v89 offset:52416
	s_waitcnt lgkmcnt(0)
	v_mfma_f32_16x16x32_bf16 v[36:39], v[28:31], v[24:27], v[36:39]
	ds_read_b128 v[28:31], v88 offset:56768
	s_waitcnt lgkmcnt(0)
	v_mfma_f32_16x16x32_bf16 v[32:35], v[28:31], v[24:27], v[40:43]
	ds_read_b128 v[28:31], v90 offset:60928
	s_nop 1
	ds_read_b128 v[40:43], v88 offset:65408
	v_mfma_f32_16x16x32_bf16 v[16:19], v[16:19], v[24:27], v[94:97]
	s_waitcnt lgkmcnt(1)
	v_mfma_f32_16x16x32_bf16 v[28:31], v[28:31], v[24:27], v[44:47]
	s_waitcnt lgkmcnt(0)
	v_mfma_f32_16x16x32_bf16 v[24:27], v[40:43], v[24:27], v[48:51]
	v_lshl_add_u32 v41, v83, 8, s55
	v_sub_u32_e32 v40, 0x80, v86
	v_bitop3_b32 v43, v85, v83, 3 bitop3:0x6c
	v_cvt_f32_i32_e32 v40, v40
	v_lshl_add_u32 v43, v43, 4, v41
	ds_read_b128 v[44:47], v43
	v_bitop3_b32 v48, v84, v83, 4 bitop3:0x36
	v_mul_f32_e64 v40, -v63, v40
	v_lshl_add_u32 v63, v48, 4, v41
	ds_read_b128 v[48:51], v63
	s_waitcnt lgkmcnt(1)
	v_mfma_f32_16x16x32_bf16 v[44:47], v[44:47], v[4:7], 0
	v_exp_f32_e32 v42, v40
	v_add_u32_e32 v40, 1, v86
	v_cvt_f32_i32_e32 v40, v40
	s_waitcnt lgkmcnt(0)
	v_mfma_f32_16x16x32_bf16 v[44:47], v[48:51], v[12:15], v[44:47]
	v_bitop3_b32 v48, v84, v83, 8 bitop3:0x36
	v_lshl_add_u32 v100, v48, 4, v41
	ds_read_b128 v[48:51], v100
	s_waitcnt lgkmcnt(0)
	v_mfma_f32_16x16x32_bf16 v[44:47], v[48:51], v[0:3], v[44:47]
	v_bitop3_b32 v48, v84, v83, 12 bitop3:0x36
	v_lshl_add_u32 v83, v48, 4, v41
	ds_read_b128 v[48:51], v83
	v_mul_f32_e32 v40, v87, v40
	v_exp_f32_e32 v40, v40
	s_waitcnt lgkmcnt(0)
	v_mfma_f32_16x16x32_bf16 v[44:47], v[48:51], v[8:11], v[44:47]
	s_nop 7
	v_pk_fma_f32 v[48:49], v[40:41], v[46:47], v[22:23] op_sel_hi:[0,1,1]
	v_pk_fma_f32 v[50:51], v[40:41], v[44:45], v[20:21] op_sel_hi:[0,1,1]
	ds_read_b128 v[20:23], v43 offset:4096
	ds_read_b128 v[44:47], v63 offset:4096
	s_waitcnt lgkmcnt(1)
	v_mfma_f32_16x16x32_bf16 v[20:23], v[20:23], v[4:7], 0
	s_waitcnt lgkmcnt(0)
	v_mfma_f32_16x16x32_bf16 v[20:23], v[44:47], v[12:15], v[20:23]
	ds_read_b128 v[44:47], v100 offset:4096
	s_waitcnt lgkmcnt(0)
	v_mfma_f32_16x16x32_bf16 v[20:23], v[44:47], v[0:3], v[20:23]
	ds_read_b128 v[44:47], v83 offset:4096
	s_waitcnt lgkmcnt(0)
	v_mfma_f32_16x16x32_bf16 v[20:23], v[44:47], v[8:11], v[20:23]
	s_nop 7
	v_pk_fma_f32 v[44:45], v[40:41], v[22:23], v[18:19] op_sel_hi:[0,1,1]
	v_pk_fma_f32 v[46:47], v[40:41], v[20:21], v[16:17] op_sel_hi:[0,1,1]
	ds_read_b128 v[16:19], v43 offset:8192
	ds_read_b128 v[20:23], v63 offset:8192
	s_waitcnt lgkmcnt(1)
	v_mfma_f32_16x16x32_bf16 v[16:19], v[16:19], v[4:7], 0
	s_waitcnt lgkmcnt(0)
	v_mfma_f32_16x16x32_bf16 v[16:19], v[20:23], v[12:15], v[16:19]
	ds_read_b128 v[20:23], v100 offset:8192
	s_waitcnt lgkmcnt(0)
	v_mfma_f32_16x16x32_bf16 v[16:19], v[20:23], v[0:3], v[16:19]
	ds_read_b128 v[20:23], v83 offset:8192
	s_waitcnt lgkmcnt(0)
	v_mfma_f32_16x16x32_bf16 v[16:19], v[20:23], v[8:11], v[16:19]
	ds_read_b128 v[20:23], v63 offset:12288
	s_nop 6
	v_pk_fma_f32 v[58:59], v[40:41], v[18:19], v[58:59] op_sel_hi:[0,1,1]
	v_pk_fma_f32 v[56:57], v[40:41], v[16:17], v[56:57] op_sel_hi:[0,1,1]
	ds_read_b128 v[16:19], v43 offset:12288
	s_waitcnt lgkmcnt(0)
	v_mfma_f32_16x16x32_bf16 v[16:19], v[16:19], v[4:7], 0
	v_mfma_f32_16x16x32_bf16 v[16:19], v[20:23], v[12:15], v[16:19]
	ds_read_b128 v[20:23], v100 offset:12288
	s_waitcnt lgkmcnt(0)
	v_mfma_f32_16x16x32_bf16 v[16:19], v[20:23], v[0:3], v[16:19]
	ds_read_b128 v[20:23], v83 offset:12288
	s_waitcnt lgkmcnt(0)
	v_mfma_f32_16x16x32_bf16 v[16:19], v[20:23], v[8:11], v[16:19]
	ds_read_b128 v[20:23], v63 offset:16384
	s_nop 6
	v_pk_fma_f32 v[54:55], v[40:41], v[18:19], v[54:55] op_sel_hi:[0,1,1]
	v_pk_fma_f32 v[52:53], v[40:41], v[16:17], v[52:53] op_sel_hi:[0,1,1]
	ds_read_b128 v[16:19], v43 offset:16384
	s_waitcnt lgkmcnt(0)
	v_mfma_f32_16x16x32_bf16 v[16:19], v[16:19], v[4:7], 0
	v_mfma_f32_16x16x32_bf16 v[16:19], v[20:23], v[12:15], v[16:19]
	ds_read_b128 v[20:23], v100 offset:16384
	s_waitcnt lgkmcnt(0)
	v_mfma_f32_16x16x32_bf16 v[16:19], v[20:23], v[0:3], v[16:19]
	ds_read_b128 v[20:23], v83 offset:16384
	s_waitcnt lgkmcnt(0)
	v_mfma_f32_16x16x32_bf16 v[16:19], v[20:23], v[8:11], v[16:19]
	ds_read_b128 v[20:23], v63 offset:20480
	s_nop 6
	v_pk_fma_f32 v[84:85], v[40:41], v[18:19], v[38:39] op_sel_hi:[0,1,1]
	v_pk_fma_f32 v[86:87], v[40:41], v[16:17], v[36:37] op_sel_hi:[0,1,1]
	ds_read_b128 v[16:19], v43 offset:20480
	s_waitcnt lgkmcnt(0)
; __device__ __forceinline__ void ret_out(const bf16_t* proj, const float* cosT, const float* sinT, const float* decay, const float* gn_g, const float* gn_b,
;                         const bf16_t* states, bf16_t* mix, unsigned char* lds, int tid, int bx) {
;     ...
; #pragma unroll
;         for (int dir = 0; dir < 2; ++dir) {
;             const unsigned char* sl = lds + ST_OFF + dir * 32768 + fr * 256;
;             const float sc = dir == 0 ? __builtin_amdgcn_exp2f(lgf2 * (float)(cq + 1)) : __builtin_amdgcn_exp2f(lgb2 * (float)(128 - cq));
; #pragma unroll
;             for (int e8 = 0; e8 < 8; ++e8) {
;                 f32x4 a2 = (f32x4){0.f, 0.f, 0.f, 0.f};
; #pragma unroll
;                 for (int ks = 0; ks < 4; ++ks) a2 = __builtin_amdgcn_mfma_f32_16x16x32_bf16(*(const bf16x8*)(sl + e8 * 4096 + (((4 * ks + fq) ^ fr) << 4)), qf[ks], a2, 0, 0, 0);
;                 acc[e8] += a2 * sc;
;             }
;         }
	v_mfma_f32_16x16x32_bf16 v[16:19], v[16:19], v[4:7], 0
	v_mfma_f32_16x16x32_bf16 v[16:19], v[20:23], v[12:15], v[16:19]
	ds_read_b128 v[20:23], v100 offset:20480
	s_waitcnt lgkmcnt(0)
	v_mfma_f32_16x16x32_bf16 v[16:19], v[20:23], v[0:3], v[16:19]
	ds_read_b128 v[20:23], v83 offset:20480
	s_waitcnt lgkmcnt(0)
	v_mfma_f32_16x16x32_bf16 v[16:19], v[20:23], v[8:11], v[16:19]
	ds_read_b128 v[20:23], v63 offset:24576
	s_nop 6
	v_pk_fma_f32 v[88:89], v[40:41], v[18:19], v[34:35] op_sel_hi:[0,1,1]
	v_pk_fma_f32 v[90:91], v[40:41], v[16:17], v[32:33] op_sel_hi:[0,1,1]
	ds_read_b128 v[16:19], v43 offset:24576
	s_waitcnt lgkmcnt(0)
	v_mfma_f32_16x16x32_bf16 v[16:19], v[16:19], v[4:7], 0
	v_mfma_f32_16x16x32_bf16 v[16:19], v[20:23], v[12:15], v[16:19]
	ds_read_b128 v[20:23], v100 offset:24576
	s_waitcnt lgkmcnt(0)
	v_mfma_f32_16x16x32_bf16 v[16:19], v[20:23], v[0:3], v[16:19]
	ds_read_b128 v[20:23], v83 offset:24576
	s_waitcnt lgkmcnt(0)
	v_mfma_f32_16x16x32_bf16 v[16:19], v[20:23], v[8:11], v[16:19]
	ds_read_b128 v[20:23], v63 offset:28672
	s_nop 6
	v_pk_fma_f32 v[92:93], v[40:41], v[18:19], v[30:31] op_sel_hi:[0,1,1]
	v_pk_fma_f32 v[94:95], v[40:41], v[16:17], v[28:29] op_sel_hi:[0,1,1]
	ds_read_b128 v[16:19], v43 offset:28672
	s_waitcnt lgkmcnt(0)
	v_mfma_f32_16x16x32_bf16 v[16:19], v[16:19], v[4:7], 0
	v_mfma_f32_16x16x32_bf16 v[16:19], v[20:23], v[12:15], v[16:19]
	ds_read_b128 v[20:23], v100 offset:28672
	s_waitcnt lgkmcnt(0)
	v_mfma_f32_16x16x32_bf16 v[16:19], v[20:23], v[0:3], v[16:19]
	ds_read_b128 v[20:23], v83 offset:28672
	s_waitcnt lgkmcnt(0)
	v_mfma_f32_16x16x32_bf16 v[16:19], v[20:23], v[8:11], v[16:19]
	ds_read_b128 v[20:23], v63 offset:32768
	s_nop 6
	v_pk_fma_f32 v[96:97], v[40:41], v[18:19], v[26:27] op_sel_hi:[0,1,1]
	v_pk_fma_f32 v[98:99], v[40:41], v[16:17], v[24:25] op_sel_hi:[0,1,1]
	ds_read_b128 v[16:19], v43 offset:32768
	s_waitcnt lgkmcnt(0)
	v_mfma_f32_16x16x32_bf16 v[16:19], v[16:19], v[4:7], 0
	v_mfma_f32_16x16x32_bf16 v[16:19], v[20:23], v[12:15], v[16:19]
	ds_read_b128 v[20:23], v100 offset:32768
	s_waitcnt lgkmcnt(0)
	v_mfma_f32_16x16x32_bf16 v[16:19], v[20:23], v[0:3], v[16:19]
	ds_read_b128 v[20:23], v83 offset:32768
	s_waitcnt lgkmcnt(0)
	v_mfma_f32_16x16x32_bf16 v[16:19], v[20:23], v[8:11], v[16:19]
	ds_read_b128 v[20:23], v63 offset:36864
	s_nop 6
	v_pk_fma_f32 v[40:41], v[42:43], v[18:19], v[48:49] op_sel_hi:[0,1,1]
	v_pk_fma_f32 v[38:39], v[42:43], v[16:17], v[50:51] op_sel_hi:[0,1,1]
	ds_read_b128 v[16:19], v43 offset:36864
	s_waitcnt lgkmcnt(0)
	v_mfma_f32_16x16x32_bf16 v[16:19], v[16:19], v[4:7], 0
	ds_read_b128 v[48:51], v63 offset:57344
	v_mfma_f32_16x16x32_bf16 v[16:19], v[20:23], v[12:15], v[16:19]
	ds_read_b128 v[20:23], v100 offset:36864
	s_waitcnt lgkmcnt(0)
	v_mfma_f32_16x16x32_bf16 v[16:19], v[20:23], v[0:3], v[16:19]
	ds_read_b128 v[20:23], v83 offset:36864
	s_waitcnt lgkmcnt(0)
	v_mfma_f32_16x16x32_bf16 v[16:19], v[20:23], v[8:11], v[16:19]
	ds_read_b128 v[20:23], v63 offset:40960
	s_nop 6
	v_pk_fma_f32 v[36:37], v[42:43], v[18:19], v[44:45] op_sel_hi:[0,1,1]
	v_pk_fma_f32 v[34:35], v[42:43], v[16:17], v[46:47] op_sel_hi:[0,1,1]
	ds_read_b128 v[16:19], v43 offset:40960
	s_waitcnt lgkmcnt(0)
	v_mfma_f32_16x16x32_bf16 v[16:19], v[16:19], v[4:7], 0
	ds_read_b128 v[44:47], v63 offset:53248
	v_mfma_f32_16x16x32_bf16 v[16:19], v[20:23], v[12:15], v[16:19]
	ds_read_b128 v[20:23], v100 offset:40960
	s_waitcnt lgkmcnt(0)
	v_mfma_f32_16x16x32_bf16 v[16:19], v[20:23], v[0:3], v[16:19]
	ds_read_b128 v[20:23], v83 offset:40960
	s_waitcnt lgkmcnt(0)
	v_mfma_f32_16x16x32_bf16 v[16:19], v[20:23], v[8:11], v[16:19]
	ds_read_b128 v[20:23], v63 offset:45056
	s_nop 6
	v_pk_fma_f32 v[32:33], v[42:43], v[18:19], v[58:59] op_sel_hi:[0,1,1]
	v_pk_fma_f32 v[30:31], v[42:43], v[16:17], v[56:57] op_sel_hi:[0,1,1]
	ds_read_b128 v[16:19], v43 offset:45056
	s_waitcnt lgkmcnt(0)
	v_mfma_f32_16x16x32_bf16 v[16:19], v[16:19], v[4:7], 0
	v_lshlrev_b32_e32 v56, 16, v75
	v_and_b32_e32 v57, 0xffff0000, v75
	v_and_b32_e32 v75, 0xffff0000, v73
	v_mfma_f32_16x16x32_bf16 v[16:19], v[20:23], v[12:15], v[16:19]
	ds_read_b128 v[20:23], v100 offset:45056
	s_waitcnt lgkmcnt(0)
	v_mfma_f32_16x16x32_bf16 v[16:19], v[20:23], v[0:3], v[16:19]
	ds_read_b128 v[20:23], v83 offset:45056
	s_waitcnt lgkmcnt(0)
	v_mfma_f32_16x16x32_bf16 v[16:19], v[20:23], v[8:11], v[16:19]
	ds_read_b128 v[20:23], v63 offset:49152
	s_nop 6
	v_pk_fma_f32 v[28:29], v[42:43], v[18:19], v[54:55] op_sel_hi:[0,1,1]
	v_pk_fma_f32 v[26:27], v[42:43], v[16:17], v[52:53] op_sel_hi:[0,1,1]
	ds_read_b128 v[16:19], v43 offset:49152
	s_waitcnt lgkmcnt(0)
	v_mfma_f32_16x16x32_bf16 v[16:19], v[16:19], v[4:7], 0
	v_lshlrev_b32_e32 v52, 16, v77
	v_and_b32_e32 v53, 0xffff0000, v77
	v_mfma_f32_16x16x32_bf16 v[16:19], v[20:23], v[12:15], v[16:19]
	ds_read_b128 v[20:23], v100 offset:49152
	s_waitcnt lgkmcnt(0)
	v_mfma_f32_16x16x32_bf16 v[16:19], v[20:23], v[0:3], v[16:19]
	ds_read_b128 v[20:23], v83 offset:49152
	s_waitcnt lgkmcnt(0)
	v_mfma_f32_16x16x32_bf16 v[16:19], v[20:23], v[8:11], v[16:19]
	s_nop 7
	v_pk_fma_f32 v[24:25], v[42:43], v[18:19], v[84:85] op_sel_hi:[0,1,1]
	v_pk_fma_f32 v[22:23], v[42:43], v[16:17], v[86:87] op_sel_hi:[0,1,1]
	ds_read_b128 v[16:19], v43 offset:53248
	s_waitcnt lgkmcnt(0)
	v_mfma_f32_16x16x32_bf16 v[16:19], v[16:19], v[4:7], 0
	v_mfma_f32_16x16x32_bf16 v[16:19], v[44:47], v[12:15], v[16:19]
	ds_read_b128 v[44:47], v100 offset:53248
	s_waitcnt lgkmcnt(0)
	v_mfma_f32_16x16x32_bf16 v[16:19], v[44:47], v[0:3], v[16:19]
	ds_read_b128 v[44:47], v83 offset:53248
	s_waitcnt lgkmcnt(0)
; __device__ __forceinline__ float bf_lo(unsigned u) { return __uint_as_float(u << 16); }
; __device__ __forceinline__ float bf_hi(unsigned u) { return __uint_as_float(u & 0xffff0000u); }
; __device__ __forceinline__ float silu_f(float x) { return x * __builtin_amdgcn_rcpf(1.0f + __expf(-x)); }
; __device__ __forceinline__ void ret_out(const bf16_t* proj, const float* cosT, const float* sinT, const float* decay, const float* gn_g, const float* gn_b,
;                         const bf16_t* states, bf16_t* mix, unsigned char* lds, int tid, int bx) {
;     ...
;                 for (int ks = 0; ks < 4; ++ks) a2 = __builtin_amdgcn_mfma_f32_16x16x32_bf16(*(const bf16x8*)(sl + e8 * 4096 + (((4 * ks + fq) ^ fr) << 4)), qf[ks], a2, 0, 0, 0);
;                 acc[e8] += a2 * sc;
;             }
;         }
;         float sm = 0.f;
; #pragma unroll
;         for (int e8 = 0; e8 < 8; ++e8) sm += (acc[e8][0] + acc[e8][1]) + (acc[e8][2] + acc[e8][3]);
;         sm += __shfl_xor(sm, 16); sm += __shfl_xor(sm, 32);
;         const float mu = sm * (1.0f / 128.0f);
;         float vs = 0.f;
; #pragma unroll
;         for (int e8 = 0; e8 < 8; ++e8)
; #pragma unroll
;             for (int r = 0; r < 4; ++r) { const float dlt = acc[e8][r] - mu; vs += dlt * dlt; }
;         vs += __shfl_xor(vs, 16); vs += __shfl_xor(vs, 32);
;         const float rstd = 1.0f / sqrtf(vs * (1.0f / 128.0f) + 1e-5f);
;         bf16_t* op = mix + (size_t)(b * SEQ + tq) * 1024 + h * 128 + 4 * fq;
; #pragma unroll
;         for (int e8 = 0; e8 < 8; ++e8) {
;             const u32x2 gw = gwv[e8];
;             const float4 gg = *(const float4*)(gnl + h * 128 + 16 * e8 + 4 * fq), gb = *(const float4*)(gnl + 768 + h * 128 + 16 * e8 + 4 * fq);
;             const float y0 = ((acc[e8][0] - mu) * rstd * gg.x + gb.x) * silu_f(bf_lo(gw.x));
;             const float y1 = ((acc[e8][1] - mu) * rstd * gg.y + gb.y) * silu_f(bf_hi(gw.x));
;             const float y2 = ((acc[e8][2] - mu) * rstd * gg.z + gb.z) * silu_f(bf_lo(gw.y));
;             const float y3 = ((acc[e8][3] - mu) * rstd * gg.w + gb.w) * silu_f(bf_hi(gw.y));
	v_mfma_f32_16x16x32_bf16 v[16:19], v[44:47], v[8:11], v[16:19]
	ds_read_b128 v[44:47], v43 offset:57344
	s_nop 6
	v_pk_fma_f32 v[20:21], v[42:43], v[18:19], v[88:89] op_sel_hi:[0,1,1]
	s_waitcnt lgkmcnt(0)
	v_mfma_f32_16x16x32_bf16 v[44:47], v[44:47], v[4:7], 0
	v_fma_f32 v18, v42, v16, v90
	v_fma_f32 v19, v42, v17, v91
	v_mfma_f32_16x16x32_bf16 v[44:47], v[48:51], v[12:15], v[44:47]
	ds_read_b128 v[48:51], v100 offset:57344
	s_waitcnt lgkmcnt(0)
	v_mfma_f32_16x16x32_bf16 v[44:47], v[48:51], v[0:3], v[44:47]
	ds_read_b128 v[48:51], v83 offset:57344
	s_waitcnt lgkmcnt(0)
	v_mfma_f32_16x16x32_bf16 v[44:47], v[48:51], v[8:11], v[44:47]
	s_nop 7
	v_pk_fma_f32 v[48:49], v[42:43], v[46:47], v[92:93] op_sel_hi:[0,1,1]
	v_pk_fma_f32 v[16:17], v[42:43], v[44:45], v[94:95] op_sel_hi:[0,1,1]
	ds_read_b128 v[44:47], v43 offset:61440
	s_waitcnt lgkmcnt(0)
	v_mfma_f32_16x16x32_bf16 v[4:7], v[44:47], v[4:7], 0
	ds_read_b128 v[44:47], v63 offset:61440
	s_waitcnt lgkmcnt(0)
	v_mfma_f32_16x16x32_bf16 v[4:7], v[44:47], v[12:15], v[4:7]
	ds_read_b128 v[12:15], v100 offset:61440
	s_waitcnt lgkmcnt(0)
	v_mfma_f32_16x16x32_bf16 v[0:3], v[12:15], v[0:3], v[4:7]
	s_nop 4
	ds_read_b128 v[4:7], v83 offset:61440
	s_waitcnt lgkmcnt(0)
	v_mfma_f32_16x16x32_bf16 v[0:3], v[4:7], v[8:11], v[0:3]
	v_mov_b32_e32 v4, v38
	v_mov_b32_e32 v5, v34
	v_mov_b32_e32 v6, v39
	v_mov_b32_e32 v7, v35
	v_pk_add_f32 v[4:5], v[4:5], v[6:7]
	v_mov_b32_e32 v6, v40
	v_mov_b32_e32 v7, v36
	v_mov_b32_e32 v8, v41
	v_mov_b32_e32 v9, v37
	v_pk_add_f32 v[6:7], v[6:7], v[8:9]
	v_mov_b32_e32 v8, v30
	v_pk_add_f32 v[4:5], v[4:5], v[6:7]
	v_pk_mov_b32 v[6:7], v[30:31], v[32:33] op_sel:[1,0]
	v_mov_b32_e32 v9, v33
	v_pk_add_f32 v[6:7], v[6:7], v[8:9]
	v_add_f32_e32 v4, 0, v4
	v_pk_add_f32 v[6:7], v[6:7], v[6:7] op_sel:[0,1] op_sel_hi:[1,0]
	v_add_f32_e32 v4, v4, v5
	v_add_f32_e32 v8, v26, v27
	v_add_f32_e32 v10, v28, v29
	v_mov_b32_e32 v5, v22
	v_mov_b32_e32 v7, v23
	v_mov_b32_e32 v9, v24
	v_mov_b32_e32 v11, v25
	v_pk_add_f32 v[4:5], v[4:5], v[6:7]
	v_pk_add_f32 v[6:7], v[8:9], v[10:11]
	v_mov_b32_e32 v8, v18
	v_pk_add_f32 v[4:5], v[4:5], v[6:7]
	v_pk_mov_b32 v[6:7], v[18:19], v[20:21] op_sel:[1,0]
	v_mov_b32_e32 v9, v21
	v_pk_add_f32 v[6:7], v[6:7], v[8:9]
	v_pk_fma_f32 v[2:3], v[42:43], v[2:3], v[96:97] op_sel_hi:[0,1,1]
	v_pk_fma_f32 v[0:1], v[42:43], v[0:1], v[98:99] op_sel_hi:[0,1,1]
	v_pk_add_f32 v[4:5], v[4:5], v[4:5] op_sel:[0,1] op_sel_hi:[1,0]
	v_pk_add_f32 v[6:7], v[6:7], v[6:7] op_sel:[0,1] op_sel_hi:[1,0]
	v_add_f32_e32 v8, v16, v17
	v_add_f32_e32 v10, v48, v49
	v_mov_b32_e32 v5, v0
	v_mov_b32_e32 v7, v1
	v_mov_b32_e32 v9, v2
	v_mov_b32_e32 v11, v3
	v_pk_add_f32 v[4:5], v[4:5], v[6:7]
	v_pk_add_f32 v[6:7], v[8:9], v[10:11]
	s_nop 0
	v_pk_add_f32 v[4:5], v[4:5], v[6:7]
	s_nop 0
	v_add_f32_e32 v4, v4, v5
	ds_bpermute_b32 v5, v61, v4
	s_waitcnt lgkmcnt(0)
	v_add_f32_e32 v4, v4, v5
	ds_bpermute_b32 v5, v82, v4
	s_waitcnt lgkmcnt(0)
	v_add_f32_e32 v4, v4, v5
	v_mul_f32_e32 v14, 0x3c000000, v4
	v_pk_add_f32 v[6:7], v[48:49], v[14:15] op_sel_hi:[1,0] neg_lo:[0,1] neg_hi:[0,1]
	v_pk_add_f32 v[4:5], v[0:1], v[14:15] op_sel_hi:[1,0] neg_lo:[0,1] neg_hi:[0,1]
	v_pk_add_f32 v[2:3], v[2:3], v[14:15] op_sel_hi:[1,0] neg_lo:[0,1] neg_hi:[0,1]
	v_add_u32_e32 v15, s0, v62
	v_lshlrev_b32_e32 v48, 16, v79
	v_add_u32_e32 v83, 0x21000, v15
	v_add_u32_e32 v148, 0x21c00, v15
	v_pk_add_f32 v[62:63], v[40:41], v[14:15] op_sel_hi:[1,0] neg_lo:[0,1] neg_hi:[0,1]
	v_mul_f32_e32 v15, 0xbfb8aa3b, v48
	v_exp_f32_e32 v15, v15
	v_and_b32_e32 v49, 0xffff0000, v79
	v_lshlrev_b64 v[0:1], 11, v[80:81]
	v_pk_mul_f32 v[80:81], v[62:63], v[62:63]
	v_add_f32_e32 v15, 1.0, v15
	v_rcp_f32_e32 v50, v15
	v_mul_f32_e32 v15, 0xbfb8aa3b, v49
	v_exp_f32_e32 v15, v15
	v_pk_mul_f32 v[8:9], v[6:7], v[6:7]
	v_pk_mul_f32 v[10:11], v[4:5], v[4:5]
	v_pk_mul_f32 v[12:13], v[2:3], v[2:3]
	v_add_f32_e32 v15, 1.0, v15
	v_pk_add_f32 v[86:87], v[38:39], v[14:15] op_sel_hi:[1,0] neg_lo:[0,1] neg_hi:[0,1]
	v_lshlrev_b32_e32 v38, 16, v78
	v_rcp_f32_e32 v51, v15
	v_mul_f32_e32 v15, 0xbfb8aa3b, v38
	v_exp_f32_e32 v15, v15
	v_and_b32_e32 v39, 0xffff0000, v78
	v_pk_mul_f32 v[84:85], v[50:51], v[48:49]
	v_pk_mul_f32 v[88:89], v[86:87], v[86:87]
	v_add_f32_e32 v15, 1.0, v15
	v_rcp_f32_e32 v48, v15
	v_mul_f32_e32 v15, 0xbfb8aa3b, v39
	v_exp_f32_e32 v15, v15
	v_add_f32_e32 v88, v88, v89
	v_add_f32_e32 v80, v80, v88
	v_add_f32_e32 v80, v81, v80
	v_add_f32_e32 v15, 1.0, v15
	v_rcp_f32_e32 v49, v15
	v_pk_add_f32 v[92:93], v[36:37], v[14:15] op_sel_hi:[1,0] neg_lo:[0,1] neg_hi:[0,1]
	v_mul_f32_e32 v15, 0xbfb8aa3b, v52
	v_exp_f32_e32 v15, v15
	v_pk_mul_f32 v[94:95], v[92:93], v[92:93]
	ds_read_b128 v[40:43], v83
	ds_read_b128 v[44:47], v148
	v_pk_mul_f32 v[90:91], v[48:49], v[38:39]
	v_add_f32_e32 v15, 1.0, v15
	v_rcp_f32_e32 v54, v15
	v_mul_f32_e32 v15, 0xbfb8aa3b, v53
	v_exp_f32_e32 v15, v15
	ds_read_b128 v[36:39], v83 offset:64
	ds_read_b128 v[48:51], v148 offset:64
	v_lshl_add_u64 v[0:1], s[42:43], 0, v[0:1]
	v_lshl_add_u64 v[0:1], v[0:1], 0, s[46:47]
	v_add_f32_e32 v15, 1.0, v15
	v_pk_add_f32 v[98:99], v[34:35], v[14:15] op_sel_hi:[1,0] neg_lo:[0,1] neg_hi:[0,1]
	v_lshlrev_b32_e32 v34, 16, v76
	v_rcp_f32_e32 v55, v15
	v_mul_f32_e32 v15, 0xbfb8aa3b, v34
	v_exp_f32_e32 v15, v15
	v_and_b32_e32 v35, 0xffff0000, v76
	v_pk_mul_f32 v[96:97], v[54:55], v[52:53]
	v_pk_mul_f32 v[100:101], v[98:99], v[98:99]
	v_add_f32_e32 v15, 1.0, v15
	v_rcp_f32_e32 v52, v15
	v_mul_f32_e32 v15, 0xbfb8aa3b, v35
	v_exp_f32_e32 v15, v15
	v_add_f32_e32 v80, v100, v80
	v_add_f32_e32 v80, v101, v80
	v_add_f32_e32 v80, v94, v80
	v_add_f32_e32 v15, 1.0, v15
	v_rcp_f32_e32 v53, v15
; __device__ __forceinline__ float bf_lo(unsigned u) { return __uint_as_float(u << 16); }
; __device__ __forceinline__ float bf_hi(unsigned u) { return __uint_as_float(u & 0xffff0000u); }
; __device__ __forceinline__ float silu_f(float x) { return x * __builtin_amdgcn_rcpf(1.0f + __expf(-x)); }
; __device__ __forceinline__ void ret_out(const bf16_t* proj, const float* cosT, const float* sinT, const float* decay, const float* gn_g, const float* gn_b,
;                         const bf16_t* states, bf16_t* mix, unsigned char* lds, int tid, int bx) {
;     ...
;         float vs = 0.f;
; #pragma unroll
;         for (int e8 = 0; e8 < 8; ++e8)
; #pragma unroll
;             for (int r = 0; r < 4; ++r) { const float dlt = acc[e8][r] - mu; vs += dlt * dlt; }
;         vs += __shfl_xor(vs, 16); vs += __shfl_xor(vs, 32);
;         const float rstd = 1.0f / sqrtf(vs * (1.0f / 128.0f) + 1e-5f);
;         bf16_t* op = mix + (size_t)(b * SEQ + tq) * 1024 + h * 128 + 4 * fq;
; #pragma unroll
;         for (int e8 = 0; e8 < 8; ++e8) {
;             const u32x2 gw = gwv[e8];
;             const float4 gg = *(const float4*)(gnl + h * 128 + 16 * e8 + 4 * fq), gb = *(const float4*)(gnl + 768 + h * 128 + 16 * e8 + 4 * fq);
;             const float y0 = ((acc[e8][0] - mu) * rstd * gg.x + gb.x) * silu_f(bf_lo(gw.x));
;             const float y1 = ((acc[e8][1] - mu) * rstd * gg.y + gb.y) * silu_f(bf_hi(gw.x));
;             const float y2 = ((acc[e8][2] - mu) * rstd * gg.z + gb.z) * silu_f(bf_lo(gw.y));
;             const float y3 = ((acc[e8][3] - mu) * rstd * gg.w + gb.w) * silu_f(bf_hi(gw.y));
	v_pk_add_f32 v[104:105], v[32:33], v[14:15] op_sel_hi:[1,0] neg_lo:[0,1] neg_hi:[0,1]
	v_mul_f32_e32 v15, 0xbfb8aa3b, v56
	v_exp_f32_e32 v15, v15
	v_add_f32_e32 v80, v95, v80
	v_pk_mul_f32 v[106:107], v[104:105], v[104:105]
	v_lshl_add_u64 v[0:1], v[0:1], 0, v[154:155]
	v_add_f32_e32 v15, 1.0, v15
	v_rcp_f32_e32 v58, v15
	v_mul_f32_e32 v15, 0xbfb8aa3b, v57
	v_exp_f32_e32 v15, v15
	v_pk_mul_f32 v[102:103], v[52:53], v[34:35]
	ds_read_b128 v[32:35], v83 offset:128
	ds_read_b128 v[52:55], v148 offset:128
	v_add_f32_e32 v15, 1.0, v15
	v_pk_add_f32 v[110:111], v[30:31], v[14:15] op_sel_hi:[1,0] neg_lo:[0,1] neg_hi:[0,1]
	v_lshlrev_b32_e32 v30, 16, v74
	v_rcp_f32_e32 v59, v15
	v_mul_f32_e32 v15, 0xbfb8aa3b, v30
	v_exp_f32_e32 v15, v15
	v_and_b32_e32 v31, 0xffff0000, v74
	v_pk_mul_f32 v[108:109], v[58:59], v[56:57]
	v_lshlrev_b32_e32 v74, 16, v73
	v_add_f32_e32 v15, 1.0, v15
	v_rcp_f32_e32 v56, v15
	v_mul_f32_e32 v15, 0xbfb8aa3b, v31
	v_exp_f32_e32 v15, v15
	v_pk_mul_f32 v[112:113], v[110:111], v[110:111]
	v_add_f32_e32 v15, 1.0, v15
	v_rcp_f32_e32 v57, v15
	v_pk_add_f32 v[116:117], v[28:29], v[14:15] op_sel_hi:[1,0] neg_lo:[0,1] neg_hi:[0,1]
	v_mul_f32_e32 v15, 0xbfb8aa3b, v74
	v_exp_f32_e32 v15, v15
	v_add_f32_e32 v80, v112, v80
	v_add_f32_e32 v80, v113, v80
	v_add_f32_e32 v80, v106, v80
	v_add_f32_e32 v15, 1.0, v15
	v_rcp_f32_e32 v76, v15
	v_mul_f32_e32 v15, 0xbfb8aa3b, v75
	v_exp_f32_e32 v15, v15
	v_add_f32_e32 v80, v107, v80
	v_pk_mul_f32 v[118:119], v[116:117], v[116:117]
	v_pk_mul_f32 v[114:115], v[56:57], v[30:31]
	v_add_f32_e32 v15, 1.0, v15
	v_pk_add_f32 v[122:123], v[26:27], v[14:15] op_sel_hi:[1,0] neg_lo:[0,1] neg_hi:[0,1]
	v_lshlrev_b32_e32 v26, 16, v72
	v_rcp_f32_e32 v77, v15
	v_mul_f32_e32 v15, 0xbfb8aa3b, v26
	v_exp_f32_e32 v15, v15
	v_and_b32_e32 v27, 0xffff0000, v72
	v_pk_mul_f32 v[120:121], v[76:77], v[74:75]
	v_lshlrev_b32_e32 v76, 16, v71
	v_add_f32_e32 v15, 1.0, v15
	v_rcp_f32_e32 v72, v15
	v_mul_f32_e32 v15, 0xbfb8aa3b, v27
	v_exp_f32_e32 v15, v15
	v_and_b32_e32 v77, 0xffff0000, v71
	v_pk_mul_f32 v[124:125], v[122:123], v[122:123]
	ds_read_b128 v[28:31], v83 offset:192
	ds_read_b128 v[56:59], v148 offset:192
	v_add_f32_e32 v15, 1.0, v15
	v_rcp_f32_e32 v73, v15
	v_pk_add_f32 v[128:129], v[24:25], v[14:15] op_sel_hi:[1,0] neg_lo:[0,1] neg_hi:[0,1]
	v_mul_f32_e32 v15, 0xbfb8aa3b, v76
	v_exp_f32_e32 v15, v15
	v_add_f32_e32 v80, v124, v80
	v_add_f32_e32 v80, v125, v80
	v_add_f32_e32 v80, v118, v80
	v_add_f32_e32 v15, 1.0, v15
	v_rcp_f32_e32 v78, v15
	v_mul_f32_e32 v15, 0xbfb8aa3b, v77
	v_exp_f32_e32 v15, v15
	v_add_f32_e32 v80, v119, v80
	v_pk_mul_f32 v[130:131], v[128:129], v[128:129]
	v_pk_mul_f32 v[126:127], v[72:73], v[26:27]
	v_add_f32_e32 v15, 1.0, v15
	v_pk_add_f32 v[134:135], v[22:23], v[14:15] op_sel_hi:[1,0] neg_lo:[0,1] neg_hi:[0,1]
	v_lshlrev_b32_e32 v22, 16, v70
	v_rcp_f32_e32 v79, v15
	v_mul_f32_e32 v15, 0xbfb8aa3b, v22
	v_exp_f32_e32 v15, v15
	v_and_b32_e32 v23, 0xffff0000, v70
	v_pk_mul_f32 v[136:137], v[134:135], v[134:135]
	ds_read_b128 v[24:27], v83 offset:256
	ds_read_b128 v[72:75], v148 offset:256
	v_add_f32_e32 v15, 1.0, v15
	v_rcp_f32_e32 v70, v15
	v_mul_f32_e32 v15, 0xbfb8aa3b, v23
	v_exp_f32_e32 v15, v15
	v_add_f32_e32 v80, v136, v80
	v_add_f32_e32 v80, v137, v80
	v_add_f32_e32 v80, v130, v80
	v_add_f32_e32 v15, 1.0, v15
	v_rcp_f32_e32 v71, v15
	v_pk_add_f32 v[138:139], v[20:21], v[14:15] op_sel_hi:[1,0] neg_lo:[0,1] neg_hi:[0,1]
	v_mul_f32_e32 v15, 0xbfb8aa3b, v142
	v_exp_f32_e32 v15, v15
	v_add_f32_e32 v80, v131, v80
	v_pk_mul_f32 v[140:141], v[138:139], v[138:139]
	v_pk_mul_f32 v[132:133], v[78:79], v[76:77]
	v_add_f32_e32 v15, 1.0, v15
	v_rcp_f32_e32 v144, v15
	v_mul_f32_e32 v15, 0xbfb8aa3b, v143
	v_exp_f32_e32 v15, v15
	v_pk_mul_f32 v[70:71], v[70:71], v[22:23]
	ds_read_b128 v[20:23], v83 offset:320
	ds_read_b128 v[76:79], v148 offset:320
	v_add_f32_e32 v15, 1.0, v15
	v_rcp_f32_e32 v145, v15
	v_pk_add_f32 v[18:19], v[18:19], v[14:15] op_sel_hi:[1,0] neg_lo:[0,1] neg_hi:[0,1]
	v_mul_f32_e32 v15, 0xbfb8aa3b, v146
	v_exp_f32_e32 v15, v15
	v_pk_mul_f32 v[142:143], v[144:145], v[142:143]
	v_pk_mul_f32 v[144:145], v[18:19], v[18:19]
	v_add_f32_e32 v15, 1.0, v15
	v_rcp_f32_e32 v68, v15
	v_mul_f32_e32 v15, 0xbfb8aa3b, v147
	v_exp_f32_e32 v15, v15
	v_add_f32_e32 v80, v144, v80
	v_add_f32_e32 v80, v145, v80
	v_add_f32_e32 v80, v140, v80
	v_add_f32_e32 v15, 1.0, v15
	v_pk_add_f32 v[16:17], v[16:17], v[14:15] op_sel_hi:[1,0] neg_lo:[0,1] neg_hi:[0,1]
	v_rcp_f32_e32 v69, v15
	v_pk_mul_f32 v[14:15], v[16:17], v[16:17]
	v_add_f32_e32 v80, v141, v80
	v_add_f32_e32 v14, v14, v80
	v_add_f32_e32 v14, v15, v14
	v_add_f32_e32 v8, v8, v14
	v_add_f32_e32 v8, v9, v8
	v_add_f32_e32 v8, v10, v8
	v_add_f32_e32 v8, v11, v8
	v_add_f32_e32 v8, v12, v8
	v_add_f32_e32 v8, v13, v8
	ds_bpermute_b32 v9, v61, v8
	v_pk_mul_f32 v[68:69], v[68:69], v[146:147]
	s_waitcnt lgkmcnt(0)
	v_add_f32_e32 v8, v8, v9
	ds_bpermute_b32 v9, v82, v8
	s_waitcnt lgkmcnt(0)
; __device__ __forceinline__ float bf_lo(unsigned u) { return __uint_as_float(u << 16); }
; __device__ __forceinline__ float bf_hi(unsigned u) { return __uint_as_float(u & 0xffff0000u); }
; __device__ __forceinline__ float silu_f(float x) { return x * __builtin_amdgcn_rcpf(1.0f + __expf(-x)); }
; __device__ __forceinline__ void ret_out(const bf16_t* proj, const float* cosT, const float* sinT, const float* decay, const float* gn_g, const float* gn_b,
;                         const bf16_t* states, bf16_t* mix, unsigned char* lds, int tid, int bx) {
;     ...
;         vs += __shfl_xor(vs, 16); vs += __shfl_xor(vs, 32);
;         const float rstd = 1.0f / sqrtf(vs * (1.0f / 128.0f) + 1e-5f);
;         bf16_t* op = mix + (size_t)(b * SEQ + tq) * 1024 + h * 128 + 4 * fq;
; #pragma unroll
;         for (int e8 = 0; e8 < 8; ++e8) {
;             const u32x2 gw = gwv[e8];
;             const float4 gg = *(const float4*)(gnl + h * 128 + 16 * e8 + 4 * fq), gb = *(const float4*)(gnl + 768 + h * 128 + 16 * e8 + 4 * fq);
;             const float y0 = ((acc[e8][0] - mu) * rstd * gg.x + gb.x) * silu_f(bf_lo(gw.x));
;             const float y1 = ((acc[e8][1] - mu) * rstd * gg.y + gb.y) * silu_f(bf_hi(gw.x));
;             const float y2 = ((acc[e8][2] - mu) * rstd * gg.z + gb.z) * silu_f(bf_lo(gw.y));
;             const float y3 = ((acc[e8][3] - mu) * rstd * gg.w + gb.w) * silu_f(bf_hi(gw.y));
;             u32x2 w; w.x = cvt_pk_bf16(y0, y1); w.y = cvt_pk_bf16(y2, y3);
;             *(u32x2*)(op + 16 * e8) = w;
;         }
	v_add_f32_e32 v8, v8, v9
	v_fmamk_f32 v8, v8, 0x3c000000, v175
	v_cmp_gt_f32_e32 vcc, s64, v8
	v_mul_f32_e32 v9, 0x4f800000, v8
	s_nop 0
	v_cndmask_b32_e32 v8, v8, v9, vcc
	v_sqrt_f32_e32 v9, v8
	s_nop 0
	v_add_u32_e32 v10, -1, v9
	v_fma_f32 v11, -v10, v9, v8
	v_cmp_ge_f32_e64 s[36:37], 0, v11
	v_add_u32_e32 v11, 1, v9
	s_nop 0
	v_cndmask_b32_e64 v10, v9, v10, s[36:37]
	v_fma_f32 v9, -v11, v9, v8
	v_cmp_lt_f32_e64 s[36:37], 0, v9
	s_nop 1
	v_cndmask_b32_e64 v9, v10, v11, s[36:37]
	v_mul_f32_e32 v10, 0x37800000, v9
	v_cndmask_b32_e32 v9, v9, v10, vcc
	v_cmp_class_f32_e32 vcc, v8, v176
	s_nop 1
	v_cndmask_b32_e32 v8, v9, v8, vcc
	v_div_scale_f32 v9, s[0:1], v8, v8, 1.0
	v_rcp_f32_e32 v10, v9
	s_nop 0
	v_fma_f32 v11, -v9, v10, 1.0
	v_fmac_f32_e32 v10, v11, v10
	v_div_scale_f32 v11, vcc, 1.0, v8, 1.0
	v_mul_f32_e32 v12, v11, v10
	v_fma_f32 v13, -v9, v12, v11
	v_fmac_f32_e32 v12, v13, v10
	v_fma_f32 v9, -v9, v12, v11
	v_div_fmas_f32 v9, v9, v10, v12
	v_div_fixup_f32 v80, v9, v8, 1.0
	v_pk_mul_f32 v[8:9], v[86:87], v[80:81] op_sel_hi:[1,0]
	v_pk_mul_f32 v[10:11], v[62:63], v[80:81] op_sel_hi:[1,0]
	v_pk_fma_f32 v[8:9], v[40:41], v[8:9], v[44:45]
	v_pk_fma_f32 v[10:11], v[42:43], v[10:11], v[46:47]
	v_pk_mul_f32 v[8:9], v[90:91], v[8:9]
	v_pk_mul_f32 v[10:11], v[84:85], v[10:11]
	v_cvt_pk_bf16_f32 v8, v8, v9
	v_cvt_pk_bf16_f32 v9, v10, v11
	global_store_dwordx2 v[0:1], v[8:9], off
	v_pk_mul_f32 v[8:9], v[98:99], v[80:81] op_sel_hi:[1,0]
	v_pk_mul_f32 v[10:11], v[92:93], v[80:81] op_sel_hi:[1,0]
	v_pk_fma_f32 v[8:9], v[36:37], v[8:9], v[48:49]
	v_pk_fma_f32 v[10:11], v[38:39], v[10:11], v[50:51]
	v_pk_mul_f32 v[8:9], v[102:103], v[8:9]
	v_pk_mul_f32 v[10:11], v[96:97], v[10:11]
	v_cvt_pk_bf16_f32 v8, v8, v9
	v_cvt_pk_bf16_f32 v9, v10, v11
	global_store_dwordx2 v[0:1], v[8:9], off offset:32
	v_pk_mul_f32 v[8:9], v[110:111], v[80:81] op_sel_hi:[1,0]
	v_pk_mul_f32 v[10:11], v[104:105], v[80:81] op_sel_hi:[1,0]
	v_pk_fma_f32 v[8:9], v[32:33], v[8:9], v[52:53]
	v_pk_fma_f32 v[10:11], v[34:35], v[10:11], v[54:55]
	v_pk_mul_f32 v[8:9], v[114:115], v[8:9]
	v_pk_mul_f32 v[10:11], v[108:109], v[10:11]
	v_cvt_pk_bf16_f32 v8, v8, v9
	v_cvt_pk_bf16_f32 v9, v10, v11
	global_store_dwordx2 v[0:1], v[8:9], off offset:64
	v_pk_mul_f32 v[8:9], v[122:123], v[80:81] op_sel_hi:[1,0]
	v_pk_mul_f32 v[10:11], v[116:117], v[80:81] op_sel_hi:[1,0]
	v_pk_fma_f32 v[8:9], v[28:29], v[8:9], v[56:57]
	v_pk_fma_f32 v[10:11], v[30:31], v[10:11], v[58:59]
	v_pk_mul_f32 v[8:9], v[126:127], v[8:9]
	v_pk_mul_f32 v[10:11], v[120:121], v[10:11]
	v_cvt_pk_bf16_f32 v8, v8, v9
	v_cvt_pk_bf16_f32 v9, v10, v11
	global_store_dwordx2 v[0:1], v[8:9], off offset:96
	v_pk_mul_f32 v[8:9], v[134:135], v[80:81] op_sel_hi:[1,0]
	v_pk_mul_f32 v[10:11], v[128:129], v[80:81] op_sel_hi:[1,0]
	v_pk_fma_f32 v[8:9], v[24:25], v[8:9], v[72:73]
	v_pk_fma_f32 v[10:11], v[26:27], v[10:11], v[74:75]
	v_pk_mul_f32 v[8:9], v[70:71], v[8:9]
	v_pk_mul_f32 v[10:11], v[132:133], v[10:11]
	v_cvt_pk_bf16_f32 v8, v8, v9
	v_cvt_pk_bf16_f32 v9, v10, v11
	global_store_dwordx2 v[0:1], v[8:9], off offset:128
	v_pk_mul_f32 v[8:9], v[18:19], v[80:81] op_sel_hi:[1,0]
	v_pk_mul_f32 v[10:11], v[138:139], v[80:81] op_sel_hi:[1,0]
	v_pk_fma_f32 v[8:9], v[20:21], v[8:9], v[76:77]
	v_pk_fma_f32 v[10:11], v[10:11], v[22:23], v[78:79]
	v_pk_mul_f32 v[8:9], v[68:69], v[8:9]
	v_pk_mul_f32 v[10:11], v[142:143], v[10:11]
	v_cvt_pk_bf16_f32 v8, v8, v9
	v_cvt_pk_bf16_f32 v9, v10, v11
	global_store_dwordx2 v[0:1], v[8:9], off offset:160
	ds_read_b128 v[8:11], v83 offset:384
	ds_read_b128 v[12:15], v148 offset:384
	s_waitcnt vmcnt(7)
	v_lshlrev_b32_e32 v18, 16, v66
	v_and_b32_e32 v19, 0xffff0000, v66
	v_pk_mul_f32 v[16:17], v[16:17], v[80:81] op_sel_hi:[1,0]
	v_mul_f32_e32 v20, 0xbfb8aa3b, v18
	s_waitcnt lgkmcnt(0)
	v_pk_fma_f32 v[8:9], v[16:17], v[8:9], v[12:13]
	v_mul_f32_e32 v12, 0xbfb8aa3b, v19
	v_exp_f32_e32 v20, v20
	v_exp_f32_e32 v12, v12
	v_pk_mul_f32 v[6:7], v[6:7], v[80:81] op_sel_hi:[1,0]
	v_pk_mul_f32 v[4:5], v[4:5], v[80:81] op_sel_hi:[1,0]
	v_add_f32_e32 v20, 1.0, v20
	v_add_f32_e32 v12, 1.0, v12
	v_rcp_f32_e32 v20, v20
	v_rcp_f32_e32 v21, v12
	v_pk_fma_f32 v[6:7], v[6:7], v[10:11], v[14:15]
	s_waitcnt vmcnt(6)
	v_lshlrev_b32_e32 v14, 16, v64
	v_and_b32_e32 v15, 0xffff0000, v64
	v_pk_mul_f32 v[12:13], v[20:21], v[18:19]
	v_pk_mul_f32 v[2:3], v[2:3], v[80:81] op_sel_hi:[1,0]
	v_pk_mul_f32 v[8:9], v[12:13], v[8:9]
	v_lshlrev_b32_e32 v12, 16, v67
	v_cvt_pk_bf16_f32 v8, v8, v9
	v_mul_f32_e32 v9, 0xbfb8aa3b, v12
	v_exp_f32_e32 v9, v9
	v_and_b32_e32 v13, 0xffff0000, v67
	v_add_f32_e32 v9, 1.0, v9
	v_rcp_f32_e32 v16, v9
	v_mul_f32_e32 v9, 0xbfb8aa3b, v13
	v_exp_f32_e32 v9, v9
	s_nop 0
	v_add_f32_e32 v9, 1.0, v9
	v_rcp_f32_e32 v17, v9
	s_nop 0
	v_pk_mul_f32 v[10:11], v[16:17], v[12:13]
	s_nop 0
	v_pk_mul_f32 v[6:7], v[10:11], v[6:7]
	v_mul_f32_e32 v16, 0xbfb8aa3b, v14
	v_cvt_pk_bf16_f32 v9, v6, v7
	global_store_dwordx2 v[0:1], v[8:9], off offset:192
	ds_read_b128 v[6:9], v83 offset:448
	ds_read_b128 v[10:13], v148 offset:448
	v_exp_f32_e32 v16, v16
	s_waitcnt lgkmcnt(0)
	v_pk_fma_f32 v[4:5], v[4:5], v[6:7], v[10:11]
	v_mul_f32_e32 v6, 0xbfb8aa3b, v15
	v_exp_f32_e32 v6, v6
	v_add_f32_e32 v16, 1.0, v16
	v_rcp_f32_e32 v16, v16
	v_pk_fma_f32 v[2:3], v[2:3], v[8:9], v[12:13]
	v_add_f32_e32 v6, 1.0, v6
	v_rcp_f32_e32 v17, v6
	s_nop 0
	v_pk_mul_f32 v[6:7], v[16:17], v[14:15]
	s_nop 0
	v_pk_mul_f32 v[4:5], v[6:7], v[4:5]
	v_lshlrev_b32_e32 v6, 16, v65
	v_cvt_pk_bf16_f32 v4, v4, v5
	v_mul_f32_e32 v5, 0xbfb8aa3b, v6
	v_exp_f32_e32 v5, v5
	v_and_b32_e32 v7, 0xffff0000, v65
	v_add_f32_e32 v5, 1.0, v5
	v_rcp_f32_e32 v10, v5
	v_mul_f32_e32 v5, 0xbfb8aa3b, v7
	v_exp_f32_e32 v5, v5
	s_nop 0
	v_add_f32_e32 v5, 1.0, v5
	v_rcp_f32_e32 v11, v5
	s_nop 0
	v_pk_mul_f32 v[6:7], v[10:11], v[6:7]
	s_nop 0
	v_pk_mul_f32 v[2:3], v[6:7], v[2:3]
	s_nop 0
	v_cvt_pk_bf16_f32 v5, v2, v3
	global_store_dwordx2 v[0:1], v[4:5], off offset:224
	s_cbranch_scc1 .LBB0_189
